# loop-edge rotation: K-loop counter/pointer SALU moved ahead of the loop-back barrier in 8 GEMM loops (on top of v7)
# baseline (speedup 1.0000x reference)
.LBB0_284:
	ds_read_b128 v[128:131], v173
	ds_read_b128 v[132:135], v173 offset:1024
	ds_read_b128 v[152:155], v173 offset:2048
	ds_read_b128 v[158:161], v173 offset:3072
	ds_read_b128 v[164:167], v177
	ds_read_b128 v[180:183], v177 offset:1024
	ds_read_b128 v[186:189], v177 offset:2048
	ds_read_b128 v[190:193], v177 offset:3072
	s_add_u32 s30, s4, 0xfffc0080
	s_addc_u32 s31, s5, -1
	s_cmp_eq_u32 s82, 12
	s_cselect_b32 s35, s25, s31
	s_cselect_b32 s34, s73, s30
	s_cselect_b32 s31, s23, s81
	s_cselect_b32 s30, s74, s75
	v_lshl_add_u64 v[170:171], s[4:5], 0, v[146:147]
	s_add_i32 m0, s43, 0xc000
	ds_read_b128 v[194:197], v179
	ds_read_b128 v[198:201], v179 offset:1024
	ds_read_b128 v[202:205], v179 offset:2048
	ds_read_b128 v[206:209], v179 offset:3072
	ds_read_b128 v[210:213], v179 offset:4096
	ds_read_b128 v[214:217], v179 offset:5120
	ds_read_b128 v[218:221], v179 offset:6144
	ds_read_b128 v[222:225], v179 offset:7168
	global_load_lds_dwordx4 v[170:171], off
	v_lshl_add_u64 v[170:171], s[4:5], 0, v[144:145]
	s_add_i32 m0, s43, 0xe000
	s_nop 0
	global_load_lds_dwordx4 v[170:171], off
	s_setprio 1
	s_waitcnt lgkmcnt(0)
	v_mfma_f32_16x16x32_bf16 v[124:127], v[128:131], v[194:197], v[124:127]
	s_waitcnt vmcnt(8)
	s_waitcnt lgkmcnt(0)
	s_barrier
	v_mfma_f32_16x16x32_bf16 v[116:119], v[152:155], v[194:197], v[116:119]
	v_mfma_f32_16x16x32_bf16 v[108:111], v[128:131], v[202:205], v[108:111]
	v_mfma_f32_16x16x32_bf16 v[100:103], v[152:155], v[202:205], v[100:103]
	v_mfma_f32_16x16x32_bf16 v[92:95], v[128:131], v[210:213], v[92:95]
	v_mfma_f32_16x16x32_bf16 v[84:87], v[152:155], v[210:213], v[84:87]
	v_mfma_f32_16x16x32_bf16 v[76:79], v[128:131], v[218:221], v[76:79]
	v_mfma_f32_16x16x32_bf16 v[68:71], v[152:155], v[218:221], v[68:71]
	v_mfma_f32_16x16x32_bf16 v[120:123], v[164:167], v[194:197], v[120:123]
	v_mfma_f32_16x16x32_bf16 v[112:115], v[186:189], v[194:197], v[112:115]
	v_mfma_f32_16x16x32_bf16 v[104:107], v[164:167], v[202:205], v[104:107]
	v_mfma_f32_16x16x32_bf16 v[96:99], v[186:189], v[202:205], v[96:99]
	v_mfma_f32_16x16x32_bf16 v[88:91], v[164:167], v[210:213], v[88:91]
	v_mfma_f32_16x16x32_bf16 v[80:83], v[186:189], v[210:213], v[80:83]
	v_mfma_f32_16x16x32_bf16 v[72:75], v[164:167], v[218:221], v[72:75]
	v_mfma_f32_16x16x32_bf16 v[64:67], v[186:189], v[218:221], v[64:67]
	v_mfma_f32_16x16x32_bf16 v[124:127], v[132:135], v[198:201], v[124:127]
	v_mfma_f32_16x16x32_bf16 v[116:119], v[158:161], v[198:201], v[116:119]
	v_mfma_f32_16x16x32_bf16 v[108:111], v[132:135], v[206:209], v[108:111]
	v_mfma_f32_16x16x32_bf16 v[100:103], v[158:161], v[206:209], v[100:103]
	v_mfma_f32_16x16x32_bf16 v[92:95], v[132:135], v[214:217], v[92:95]
	v_mfma_f32_16x16x32_bf16 v[84:87], v[158:161], v[214:217], v[84:87]
	v_mfma_f32_16x16x32_bf16 v[76:79], v[132:135], v[222:225], v[76:79]
	v_mfma_f32_16x16x32_bf16 v[68:71], v[158:161], v[222:225], v[68:71]
	v_mfma_f32_16x16x32_bf16 v[120:123], v[180:183], v[198:201], v[120:123]
	v_mfma_f32_16x16x32_bf16 v[112:115], v[190:193], v[198:201], v[112:115]
	v_mfma_f32_16x16x32_bf16 v[104:107], v[180:183], v[206:209], v[104:107]
	v_mfma_f32_16x16x32_bf16 v[96:99], v[190:193], v[206:209], v[96:99]
	v_mfma_f32_16x16x32_bf16 v[88:91], v[180:183], v[214:217], v[88:91]
	v_mfma_f32_16x16x32_bf16 v[80:83], v[190:193], v[214:217], v[80:83]
	v_mfma_f32_16x16x32_bf16 v[72:75], v[180:183], v[222:225], v[72:75]
	v_mfma_f32_16x16x32_bf16 v[64:67], v[190:193], v[222:225], v[64:67]
	s_setprio 0
	s_barrier
	s_add_i32 s83, s65, s40
	v_lshl_add_u64 v[170:171], s[30:31], 0, v[140:141]
	s_mov_b32 m0, s83
	ds_read_b128 v[194:197], v179 offset:16384
	ds_read_b128 v[198:201], v179 offset:17408
	ds_read_b128 v[202:205], v179 offset:18432
	ds_read_b128 v[206:209], v179 offset:19456
	ds_read_b128 v[210:213], v179 offset:20480
	ds_read_b128 v[214:217], v179 offset:21504
	ds_read_b128 v[218:221], v179 offset:22528
	ds_read_b128 v[222:225], v179 offset:23552
	global_load_lds_dwordx4 v[170:171], off
	s_add_i32 m0, s83, 0x2000
	s_add_u32 s84, s30, 0x40000
	v_lshl_add_u64 v[174:175], s[30:31], 0, v[136:137]
	s_addc_u32 s85, s31, 0
	s_add_i32 s83, s66, s40
	global_load_lds_dwordx4 v[174:175], off
	v_lshl_add_u64 v[226:227], s[84:85], 0, v[140:141]
	s_mov_b32 m0, s83
	v_lshl_add_u64 v[230:231], s[34:35], 0, v[138:139]
	global_load_lds_dwordx4 v[226:227], off
	v_lshl_add_u64 v[226:227], s[84:85], 0, v[136:137]
	s_add_i32 m0, s83, 0x2000
	s_nop 0
	global_load_lds_dwordx4 v[226:227], off
	v_lshl_add_u64 v[226:227], s[34:35], 0, v[142:143]
	s_mov_b32 m0, s43
	s_nop 0
	global_load_lds_dwordx4 v[226:227], off
	s_mov_b32 m0, s44
	s_nop 0
	global_load_lds_dwordx4 v[230:231], off
	s_setprio 1
	s_waitcnt lgkmcnt(0)
	v_mfma_f32_16x16x32_bf16 v[60:63], v[128:131], v[194:197], v[60:63]
	s_waitcnt vmcnt(8)
	s_waitcnt lgkmcnt(0)
	s_barrier
	v_mfma_f32_16x16x32_bf16 v[52:55], v[152:155], v[194:197], v[52:55]
	v_mfma_f32_16x16x32_bf16 v[44:47], v[128:131], v[202:205], v[44:47]
	v_mfma_f32_16x16x32_bf16 v[36:39], v[152:155], v[202:205], v[36:39]
	v_mfma_f32_16x16x32_bf16 v[28:31], v[128:131], v[210:213], v[28:31]
	v_mfma_f32_16x16x32_bf16 v[20:23], v[152:155], v[210:213], v[20:23]
	v_mfma_f32_16x16x32_bf16 v[12:15], v[128:131], v[218:221], v[12:15]
	v_mfma_f32_16x16x32_bf16 v[4:7], v[152:155], v[218:221], v[4:7]
	v_mfma_f32_16x16x32_bf16 v[56:59], v[164:167], v[194:197], v[56:59]
	v_mfma_f32_16x16x32_bf16 v[48:51], v[186:189], v[194:197], v[48:51]
	v_mfma_f32_16x16x32_bf16 v[40:43], v[164:167], v[202:205], v[40:43]
	v_mfma_f32_16x16x32_bf16 v[32:35], v[186:189], v[202:205], v[32:35]
	v_mfma_f32_16x16x32_bf16 v[24:27], v[164:167], v[210:213], v[24:27]
	v_mfma_f32_16x16x32_bf16 v[16:19], v[186:189], v[210:213], v[16:19]
	v_mfma_f32_16x16x32_bf16 v[8:11], v[164:167], v[218:221], v[8:11]
	v_mfma_f32_16x16x32_bf16 v[0:3], v[186:189], v[218:221], v[0:3]
	v_mfma_f32_16x16x32_bf16 v[60:63], v[132:135], v[198:201], v[60:63]
	v_mfma_f32_16x16x32_bf16 v[52:55], v[158:161], v[198:201], v[52:55]
	v_mfma_f32_16x16x32_bf16 v[44:47], v[132:135], v[206:209], v[44:47]
	v_mfma_f32_16x16x32_bf16 v[36:39], v[158:161], v[206:209], v[36:39]
	v_mfma_f32_16x16x32_bf16 v[28:31], v[132:135], v[214:217], v[28:31]
	v_mfma_f32_16x16x32_bf16 v[20:23], v[158:161], v[214:217], v[20:23]
	v_mfma_f32_16x16x32_bf16 v[12:15], v[132:135], v[222:225], v[12:15]
	v_mfma_f32_16x16x32_bf16 v[4:7], v[158:161], v[222:225], v[4:7]
	v_mfma_f32_16x16x32_bf16 v[56:59], v[180:183], v[198:201], v[56:59]
	v_mfma_f32_16x16x32_bf16 v[48:51], v[190:193], v[198:201], v[48:51]
	v_mfma_f32_16x16x32_bf16 v[40:43], v[180:183], v[206:209], v[40:43]
	v_mfma_f32_16x16x32_bf16 v[32:35], v[190:193], v[206:209], v[32:35]
	v_mfma_f32_16x16x32_bf16 v[24:27], v[180:183], v[214:217], v[24:27]
	v_mfma_f32_16x16x32_bf16 v[16:19], v[190:193], v[214:217], v[16:19]
	v_mfma_f32_16x16x32_bf16 v[8:11], v[180:183], v[222:225], v[8:11]
	v_mfma_f32_16x16x32_bf16 v[0:3], v[190:193], v[222:225], v[0:3]
	s_setprio 0
	s_barrier
	s_add_i32 s83, 0, 0x18000
	v_add_u32_e32 v156, s83, v169
	s_add_i32 s84, 0, 0x1c000
	ds_read_b128 v[128:131], v156
	ds_read_b128 v[132:135], v156 offset:1024
	ds_read_b128 v[152:155], v156 offset:2048
	ds_read_b128 v[158:161], v156 offset:3072
	v_add_u32_e32 v156, s84, v169
	ds_read_b128 v[164:167], v156
	ds_read_b128 v[180:183], v156 offset:1024
	ds_read_b128 v[186:189], v156 offset:2048
	ds_read_b128 v[190:193], v156 offset:3072
	s_add_u32 s34, s34, 0x40000
	s_addc_u32 s35, s35, 0
	s_mov_b32 m0, s45
	v_lshl_add_u64 v[232:233], s[34:35], 0, v[142:143]
	ds_read_b128 v[194:197], v179 offset:32768
	ds_read_b128 v[198:201], v179 offset:33792
	ds_read_b128 v[202:205], v179 offset:34816
	ds_read_b128 v[206:209], v179 offset:35840
	ds_read_b128 v[210:213], v179 offset:36864
	ds_read_b128 v[214:217], v179 offset:37888
	ds_read_b128 v[218:221], v179 offset:38912
	ds_read_b128 v[222:225], v179 offset:39936
	global_load_lds_dwordx4 v[232:233], off
	v_lshl_add_u64 v[232:233], s[34:35], 0, v[138:139]
	s_mov_b32 m0, s55
	s_nop 0
	global_load_lds_dwordx4 v[232:233], off
	s_setprio 1
	s_waitcnt lgkmcnt(0)
	v_mfma_f32_16x16x32_bf16 v[124:127], v[128:131], v[194:197], v[124:127]
	s_waitcnt vmcnt(8)
	s_waitcnt lgkmcnt(0)
	s_barrier
	v_mfma_f32_16x16x32_bf16 v[116:119], v[152:155], v[194:197], v[116:119]
	v_mfma_f32_16x16x32_bf16 v[108:111], v[128:131], v[202:205], v[108:111]
	v_mfma_f32_16x16x32_bf16 v[100:103], v[152:155], v[202:205], v[100:103]
	v_mfma_f32_16x16x32_bf16 v[92:95], v[128:131], v[210:213], v[92:95]
	v_mfma_f32_16x16x32_bf16 v[84:87], v[152:155], v[210:213], v[84:87]
	v_mfma_f32_16x16x32_bf16 v[76:79], v[128:131], v[218:221], v[76:79]
	v_mfma_f32_16x16x32_bf16 v[68:71], v[152:155], v[218:221], v[68:71]
	v_mfma_f32_16x16x32_bf16 v[120:123], v[164:167], v[194:197], v[120:123]
	v_mfma_f32_16x16x32_bf16 v[112:115], v[186:189], v[194:197], v[112:115]
	v_mfma_f32_16x16x32_bf16 v[104:107], v[164:167], v[202:205], v[104:107]
	v_mfma_f32_16x16x32_bf16 v[96:99], v[186:189], v[202:205], v[96:99]
	v_mfma_f32_16x16x32_bf16 v[88:91], v[164:167], v[210:213], v[88:91]
	v_mfma_f32_16x16x32_bf16 v[80:83], v[186:189], v[210:213], v[80:83]
	v_mfma_f32_16x16x32_bf16 v[72:75], v[164:167], v[218:221], v[72:75]
	v_mfma_f32_16x16x32_bf16 v[64:67], v[186:189], v[218:221], v[64:67]
	v_mfma_f32_16x16x32_bf16 v[124:127], v[132:135], v[198:201], v[124:127]
	v_mfma_f32_16x16x32_bf16 v[116:119], v[158:161], v[198:201], v[116:119]
	v_mfma_f32_16x16x32_bf16 v[108:111], v[132:135], v[206:209], v[108:111]
	v_mfma_f32_16x16x32_bf16 v[100:103], v[158:161], v[206:209], v[100:103]
	v_mfma_f32_16x16x32_bf16 v[92:95], v[132:135], v[214:217], v[92:95]
	v_mfma_f32_16x16x32_bf16 v[84:87], v[158:161], v[214:217], v[84:87]
	v_mfma_f32_16x16x32_bf16 v[76:79], v[132:135], v[222:225], v[76:79]
	v_mfma_f32_16x16x32_bf16 v[68:71], v[158:161], v[222:225], v[68:71]
	v_mfma_f32_16x16x32_bf16 v[120:123], v[180:183], v[198:201], v[120:123]
	v_mfma_f32_16x16x32_bf16 v[112:115], v[190:193], v[198:201], v[112:115]
	v_mfma_f32_16x16x32_bf16 v[104:107], v[180:183], v[206:209], v[104:107]
	v_mfma_f32_16x16x32_bf16 v[96:99], v[190:193], v[206:209], v[96:99]
	v_mfma_f32_16x16x32_bf16 v[88:91], v[180:183], v[214:217], v[88:91]
	v_mfma_f32_16x16x32_bf16 v[80:83], v[190:193], v[214:217], v[80:83]
	v_mfma_f32_16x16x32_bf16 v[72:75], v[180:183], v[222:225], v[72:75]
	v_mfma_f32_16x16x32_bf16 v[64:67], v[190:193], v[222:225], v[64:67]
	s_setprio 0
	s_barrier
	s_add_i32 s34, s83, s40
	v_lshl_add_u64 v[170:171], v[170:171], 0, s[12:13]
	s_mov_b32 m0, s34
	ds_read_b128 v[194:197], v179 offset:49152
	ds_read_b128 v[198:201], v179 offset:50176
	ds_read_b128 v[202:205], v179 offset:51200
	ds_read_b128 v[206:209], v179 offset:52224
	ds_read_b128 v[210:213], v179 offset:53248
	ds_read_b128 v[214:217], v179 offset:54272
	ds_read_b128 v[218:221], v179 offset:55296
	ds_read_b128 v[222:225], v179 offset:56320
	global_load_lds_dwordx4 v[170:171], off
	s_add_i32 m0, s34, 0x2000
	s_add_u32 s30, s30, 0x40080
	v_lshl_add_u64 v[170:171], v[174:175], 0, s[12:13]
	s_addc_u32 s31, s31, 0
	s_add_i32 s34, s84, s40
	global_load_lds_dwordx4 v[170:171], off
	v_lshl_add_u64 v[170:171], s[30:31], 0, v[140:141]
	s_mov_b32 m0, s34
	s_nop 0
	global_load_lds_dwordx4 v[170:171], off
	v_lshl_add_u64 v[170:171], s[30:31], 0, v[136:137]
	s_add_i32 m0, s34, 0x2000
	s_nop 0
	global_load_lds_dwordx4 v[170:171], off
	v_lshl_add_u64 v[170:171], v[226:227], 0, s[12:13]
	s_mov_b32 m0, s62
	s_nop 0
	global_load_lds_dwordx4 v[170:171], off
	v_lshl_add_u64 v[170:171], v[230:231], 0, s[12:13]
	s_mov_b32 m0, s63
	s_nop 0
	global_load_lds_dwordx4 v[170:171], off
	s_setprio 1
	s_waitcnt lgkmcnt(0)
	v_mfma_f32_16x16x32_bf16 v[60:63], v[128:131], v[194:197], v[60:63]
	s_waitcnt vmcnt(8)
	s_waitcnt lgkmcnt(0)
	s_barrier
	v_mfma_f32_16x16x32_bf16 v[52:55], v[152:155], v[194:197], v[52:55]
	v_mfma_f32_16x16x32_bf16 v[44:47], v[128:131], v[202:205], v[44:47]
	v_mfma_f32_16x16x32_bf16 v[36:39], v[152:155], v[202:205], v[36:39]
	v_mfma_f32_16x16x32_bf16 v[28:31], v[128:131], v[210:213], v[28:31]
	v_mfma_f32_16x16x32_bf16 v[20:23], v[152:155], v[210:213], v[20:23]
	v_mfma_f32_16x16x32_bf16 v[12:15], v[128:131], v[218:221], v[12:15]
	v_mfma_f32_16x16x32_bf16 v[4:7], v[152:155], v[218:221], v[4:7]
	v_mfma_f32_16x16x32_bf16 v[56:59], v[164:167], v[194:197], v[56:59]
	v_mfma_f32_16x16x32_bf16 v[48:51], v[186:189], v[194:197], v[48:51]
	v_mfma_f32_16x16x32_bf16 v[40:43], v[164:167], v[202:205], v[40:43]
	v_mfma_f32_16x16x32_bf16 v[32:35], v[186:189], v[202:205], v[32:35]
	v_mfma_f32_16x16x32_bf16 v[24:27], v[164:167], v[210:213], v[24:27]
	v_mfma_f32_16x16x32_bf16 v[16:19], v[186:189], v[210:213], v[16:19]
	v_mfma_f32_16x16x32_bf16 v[8:11], v[164:167], v[218:221], v[8:11]
	v_mfma_f32_16x16x32_bf16 v[0:3], v[186:189], v[218:221], v[0:3]
	v_mfma_f32_16x16x32_bf16 v[60:63], v[132:135], v[198:201], v[60:63]
	v_mfma_f32_16x16x32_bf16 v[52:55], v[158:161], v[198:201], v[52:55]
	v_mfma_f32_16x16x32_bf16 v[44:47], v[132:135], v[206:209], v[44:47]
	v_mfma_f32_16x16x32_bf16 v[36:39], v[158:161], v[206:209], v[36:39]
	v_mfma_f32_16x16x32_bf16 v[28:31], v[132:135], v[214:217], v[28:31]
	v_mfma_f32_16x16x32_bf16 v[20:23], v[158:161], v[214:217], v[20:23]
	v_mfma_f32_16x16x32_bf16 v[12:15], v[132:135], v[222:225], v[12:15]
	v_mfma_f32_16x16x32_bf16 v[4:7], v[158:161], v[222:225], v[4:7]
	v_mfma_f32_16x16x32_bf16 v[56:59], v[180:183], v[198:201], v[56:59]
	v_mfma_f32_16x16x32_bf16 v[48:51], v[190:193], v[198:201], v[48:51]
	v_mfma_f32_16x16x32_bf16 v[40:43], v[180:183], v[206:209], v[40:43]
	v_mfma_f32_16x16x32_bf16 v[32:35], v[190:193], v[206:209], v[32:35]
	v_mfma_f32_16x16x32_bf16 v[24:27], v[180:183], v[214:217], v[24:27]
	v_mfma_f32_16x16x32_bf16 v[16:19], v[190:193], v[214:217], v[16:19]
	v_mfma_f32_16x16x32_bf16 v[8:11], v[180:183], v[222:225], v[8:11]
	v_mfma_f32_16x16x32_bf16 v[0:3], v[190:193], v[222:225], v[0:3]
	s_setprio 0
	s_add_i32 s82, s82, 2
	s_add_u32 s75, s75, 0x100
	s_addc_u32 s81, s81, 0
	s_add_u32 s4, s4, 0x100
	s_addc_u32 s5, s5, 0
	s_cmp_gt_u32 s82, 13
	s_barrier
	s_cbranch_scc0 .LBB0_284
	s_and_b64 vcc, exec, s[14:15]
	s_cbranch_vccz .LBB0_287
	s_barrier

.LBB0_358:
	ds_read_b128 v[96:99], v233
	ds_read_b128 v[100:103], v233 offset:1024
	ds_read_b128 v[152:155], v233 offset:2048
	ds_read_b128 v[156:159], v233 offset:3072
	ds_read_b128 v[160:163], v234
	ds_read_b128 v[164:167], v234 offset:1024
	ds_read_b128 v[168:171], v234 offset:2048
	ds_read_b128 v[172:175], v234 offset:3072
	s_add_u32 s20, s18, 0x100
	s_addc_u32 s21, s19, 0
	s_cmp_eq_u32 s73, 40
	s_cselect_b32 s25, s5, s21
	s_cselect_b32 s24, s4, s20
	s_cselect_b32 s23, s17, s72
	s_cselect_b32 s22, s16, s67
	v_lshl_add_u64 v[208:209], s[18:19], 0, v[146:147]
	s_add_i32 m0, s31, 0xc000
	ds_read_b128 v[176:179], v235
	ds_read_b128 v[180:183], v235 offset:1024
	ds_read_b128 v[184:187], v235 offset:2048
	ds_read_b128 v[188:191], v235 offset:3072
	ds_read_b128 v[192:195], v235 offset:4096
	ds_read_b128 v[196:199], v235 offset:5120
	ds_read_b128 v[200:203], v235 offset:6144
	ds_read_b128 v[204:207], v235 offset:7168
	global_load_lds_dwordx4 v[208:209], off
	v_lshl_add_u64 v[208:209], s[18:19], 0, v[144:145]
	s_add_i32 m0, s31, 0xe000
	s_nop 0
	global_load_lds_dwordx4 v[208:209], off
	s_setprio 1
	s_waitcnt lgkmcnt(0)
	v_mfma_f32_16x16x32_bf16 v[132:135], v[96:99], v[176:179], v[132:135]
	s_waitcnt vmcnt(8)
	s_waitcnt lgkmcnt(0)
	s_barrier
	v_mfma_f32_16x16x32_bf16 v[128:131], v[152:155], v[176:179], v[128:131]
	v_mfma_f32_16x16x32_bf16 v[124:127], v[96:99], v[184:187], v[124:127]
	v_mfma_f32_16x16x32_bf16 v[120:123], v[152:155], v[184:187], v[120:123]
	v_mfma_f32_16x16x32_bf16 v[116:119], v[96:99], v[192:195], v[116:119]
	v_mfma_f32_16x16x32_bf16 v[112:115], v[152:155], v[192:195], v[112:115]
	v_mfma_f32_16x16x32_bf16 v[108:111], v[96:99], v[200:203], v[108:111]
	v_mfma_f32_16x16x32_bf16 v[104:107], v[152:155], v[200:203], v[104:107]
	v_mfma_f32_16x16x32_bf16 v[60:63], v[160:163], v[176:179], v[60:63]
	v_mfma_f32_16x16x32_bf16 v[56:59], v[168:171], v[176:179], v[56:59]
	v_mfma_f32_16x16x32_bf16 v[52:55], v[160:163], v[184:187], v[52:55]
	v_mfma_f32_16x16x32_bf16 v[48:51], v[168:171], v[184:187], v[48:51]
	v_mfma_f32_16x16x32_bf16 v[44:47], v[160:163], v[192:195], v[44:47]
	v_mfma_f32_16x16x32_bf16 v[40:43], v[168:171], v[192:195], v[40:43]
	v_mfma_f32_16x16x32_bf16 v[36:39], v[160:163], v[200:203], v[36:39]
	v_mfma_f32_16x16x32_bf16 v[32:35], v[168:171], v[200:203], v[32:35]
	v_mfma_f32_16x16x32_bf16 v[132:135], v[100:103], v[180:183], v[132:135]
	v_mfma_f32_16x16x32_bf16 v[128:131], v[156:159], v[180:183], v[128:131]
	v_mfma_f32_16x16x32_bf16 v[124:127], v[100:103], v[188:191], v[124:127]
	v_mfma_f32_16x16x32_bf16 v[120:123], v[156:159], v[188:191], v[120:123]
	v_mfma_f32_16x16x32_bf16 v[116:119], v[100:103], v[196:199], v[116:119]
	v_mfma_f32_16x16x32_bf16 v[112:115], v[156:159], v[196:199], v[112:115]
	v_mfma_f32_16x16x32_bf16 v[108:111], v[100:103], v[204:207], v[108:111]
	v_mfma_f32_16x16x32_bf16 v[104:107], v[156:159], v[204:207], v[104:107]
	v_mfma_f32_16x16x32_bf16 v[60:63], v[164:167], v[180:183], v[60:63]
	v_mfma_f32_16x16x32_bf16 v[56:59], v[172:175], v[180:183], v[56:59]
	v_mfma_f32_16x16x32_bf16 v[52:55], v[164:167], v[188:191], v[52:55]
	v_mfma_f32_16x16x32_bf16 v[48:51], v[172:175], v[188:191], v[48:51]
	v_mfma_f32_16x16x32_bf16 v[44:47], v[164:167], v[196:199], v[44:47]
	v_mfma_f32_16x16x32_bf16 v[40:43], v[172:175], v[196:199], v[40:43]
	v_mfma_f32_16x16x32_bf16 v[36:39], v[164:167], v[204:207], v[36:39]
	v_mfma_f32_16x16x32_bf16 v[32:35], v[172:175], v[204:207], v[32:35]
	s_setprio 0
	s_barrier
	s_add_i32 s18, s61, s30
	v_lshl_add_u64 v[208:209], s[22:23], 0, v[138:139]
	s_mov_b32 m0, s18
	ds_read_b128 v[176:179], v235 offset:16384
	ds_read_b128 v[180:183], v235 offset:17408
	ds_read_b128 v[184:187], v235 offset:18432
	ds_read_b128 v[188:191], v235 offset:19456
	ds_read_b128 v[192:195], v235 offset:20480
	ds_read_b128 v[196:199], v235 offset:21504
	ds_read_b128 v[200:203], v235 offset:22528
	ds_read_b128 v[204:207], v235 offset:23552
	global_load_lds_dwordx4 v[208:209], off
	s_add_i32 m0, s18, 0x2000
	s_add_u32 s18, s22, 0xb0000
	v_lshl_add_u64 v[210:211], s[22:23], 0, v[142:143]
	s_addc_u32 s19, s23, 0
	s_add_i32 s74, s62, s30
	global_load_lds_dwordx4 v[210:211], off
	v_lshl_add_u64 v[212:213], s[18:19], 0, v[138:139]
	s_mov_b32 m0, s74
	v_lshl_add_u64 v[214:215], s[24:25], 0, v[140:141]
	global_load_lds_dwordx4 v[212:213], off
	v_lshl_add_u64 v[212:213], s[18:19], 0, v[142:143]
	s_add_i32 m0, s74, 0x2000
	s_nop 0
	global_load_lds_dwordx4 v[212:213], off
	v_lshl_add_u64 v[212:213], s[24:25], 0, v[136:137]
	s_mov_b32 m0, s31
	s_nop 0
	global_load_lds_dwordx4 v[212:213], off
	s_mov_b32 m0, s34
	s_nop 0
	global_load_lds_dwordx4 v[214:215], off
	s_setprio 1
	s_waitcnt lgkmcnt(0)
	v_mfma_f32_16x16x32_bf16 v[92:95], v[96:99], v[176:179], v[92:95]
	s_waitcnt vmcnt(8)
	s_waitcnt lgkmcnt(0)
	s_barrier
	v_mfma_f32_16x16x32_bf16 v[88:91], v[152:155], v[176:179], v[88:91]
	v_mfma_f32_16x16x32_bf16 v[84:87], v[96:99], v[184:187], v[84:87]
	v_mfma_f32_16x16x32_bf16 v[80:83], v[152:155], v[184:187], v[80:83]
	v_mfma_f32_16x16x32_bf16 v[76:79], v[96:99], v[192:195], v[76:79]
	v_mfma_f32_16x16x32_bf16 v[72:75], v[152:155], v[192:195], v[72:75]
	v_mfma_f32_16x16x32_bf16 v[68:71], v[96:99], v[200:203], v[68:71]
	v_mfma_f32_16x16x32_bf16 v[64:67], v[152:155], v[200:203], v[64:67]
	v_mfma_f32_16x16x32_bf16 v[28:31], v[160:163], v[176:179], v[28:31]
	v_mfma_f32_16x16x32_bf16 v[24:27], v[168:171], v[176:179], v[24:27]
	v_mfma_f32_16x16x32_bf16 v[20:23], v[160:163], v[184:187], v[20:23]
	v_mfma_f32_16x16x32_bf16 v[16:19], v[168:171], v[184:187], v[16:19]
	v_mfma_f32_16x16x32_bf16 v[12:15], v[160:163], v[192:195], v[12:15]
	v_mfma_f32_16x16x32_bf16 v[8:11], v[168:171], v[192:195], v[8:11]
	v_mfma_f32_16x16x32_bf16 v[4:7], v[160:163], v[200:203], v[4:7]
	v_mfma_f32_16x16x32_bf16 v[0:3], v[168:171], v[200:203], v[0:3]
	v_mfma_f32_16x16x32_bf16 v[92:95], v[100:103], v[180:183], v[92:95]
	v_mfma_f32_16x16x32_bf16 v[88:91], v[156:159], v[180:183], v[88:91]
	v_mfma_f32_16x16x32_bf16 v[84:87], v[100:103], v[188:191], v[84:87]
	v_mfma_f32_16x16x32_bf16 v[80:83], v[156:159], v[188:191], v[80:83]
	v_mfma_f32_16x16x32_bf16 v[76:79], v[100:103], v[196:199], v[76:79]
	v_mfma_f32_16x16x32_bf16 v[72:75], v[156:159], v[196:199], v[72:75]
	v_mfma_f32_16x16x32_bf16 v[68:71], v[100:103], v[204:207], v[68:71]
	v_mfma_f32_16x16x32_bf16 v[64:67], v[156:159], v[204:207], v[64:67]
	v_mfma_f32_16x16x32_bf16 v[28:31], v[164:167], v[180:183], v[28:31]
	v_mfma_f32_16x16x32_bf16 v[24:27], v[172:175], v[180:183], v[24:27]
	v_mfma_f32_16x16x32_bf16 v[20:23], v[164:167], v[188:191], v[20:23]
	v_mfma_f32_16x16x32_bf16 v[16:19], v[172:175], v[188:191], v[16:19]
	v_mfma_f32_16x16x32_bf16 v[12:15], v[164:167], v[196:199], v[12:15]
	v_mfma_f32_16x16x32_bf16 v[8:11], v[172:175], v[196:199], v[8:11]
	v_mfma_f32_16x16x32_bf16 v[4:7], v[164:167], v[204:207], v[4:7]
	v_mfma_f32_16x16x32_bf16 v[0:3], v[172:175], v[204:207], v[0:3]
	s_setprio 0
	s_barrier
	s_add_i32 s74, 0, 0x18000
	s_add_i32 s75, 0, 0x1c000
	v_add_u32_e32 v156, s74, v232
	v_add_u32_e32 v172, s75, v232
	ds_read_b128 v[96:99], v156
	ds_read_b128 v[100:103], v156 offset:1024
	ds_read_b128 v[152:155], v156 offset:2048
	ds_read_b128 v[156:159], v156 offset:3072
	ds_read_b128 v[160:163], v172
	ds_read_b128 v[164:167], v172 offset:1024
	ds_read_b128 v[168:171], v172 offset:2048
	ds_read_b128 v[172:175], v172 offset:3072
	s_add_u32 s18, s24, 0xb0000
	s_addc_u32 s19, s25, 0
	s_mov_b32 m0, s35
	v_lshl_add_u64 v[216:217], s[18:19], 0, v[136:137]
	ds_read_b128 v[176:179], v235 offset:32768
	ds_read_b128 v[180:183], v235 offset:33792
	ds_read_b128 v[184:187], v235 offset:34816
	ds_read_b128 v[188:191], v235 offset:35840
	ds_read_b128 v[192:195], v235 offset:36864
	ds_read_b128 v[196:199], v235 offset:37888
	ds_read_b128 v[200:203], v235 offset:38912
	ds_read_b128 v[204:207], v235 offset:39936
	global_load_lds_dwordx4 v[216:217], off
	v_lshl_add_u64 v[216:217], s[18:19], 0, v[140:141]
	s_mov_b32 m0, s38
	s_nop 0
	global_load_lds_dwordx4 v[216:217], off
	s_setprio 1
	s_waitcnt lgkmcnt(0)
	v_mfma_f32_16x16x32_bf16 v[132:135], v[96:99], v[176:179], v[132:135]
	s_waitcnt vmcnt(8)
	s_waitcnt lgkmcnt(0)
	s_barrier
	v_mfma_f32_16x16x32_bf16 v[128:131], v[152:155], v[176:179], v[128:131]
	v_mfma_f32_16x16x32_bf16 v[124:127], v[96:99], v[184:187], v[124:127]
	v_mfma_f32_16x16x32_bf16 v[120:123], v[152:155], v[184:187], v[120:123]
	v_mfma_f32_16x16x32_bf16 v[116:119], v[96:99], v[192:195], v[116:119]
	v_mfma_f32_16x16x32_bf16 v[112:115], v[152:155], v[192:195], v[112:115]
	v_mfma_f32_16x16x32_bf16 v[108:111], v[96:99], v[200:203], v[108:111]
	v_mfma_f32_16x16x32_bf16 v[104:107], v[152:155], v[200:203], v[104:107]
	v_mfma_f32_16x16x32_bf16 v[60:63], v[160:163], v[176:179], v[60:63]
	v_mfma_f32_16x16x32_bf16 v[56:59], v[168:171], v[176:179], v[56:59]
	v_mfma_f32_16x16x32_bf16 v[52:55], v[160:163], v[184:187], v[52:55]
	v_mfma_f32_16x16x32_bf16 v[48:51], v[168:171], v[184:187], v[48:51]
	v_mfma_f32_16x16x32_bf16 v[44:47], v[160:163], v[192:195], v[44:47]
	v_mfma_f32_16x16x32_bf16 v[40:43], v[168:171], v[192:195], v[40:43]
	v_mfma_f32_16x16x32_bf16 v[36:39], v[160:163], v[200:203], v[36:39]
	v_mfma_f32_16x16x32_bf16 v[32:35], v[168:171], v[200:203], v[32:35]
	v_mfma_f32_16x16x32_bf16 v[132:135], v[100:103], v[180:183], v[132:135]
	v_mfma_f32_16x16x32_bf16 v[128:131], v[156:159], v[180:183], v[128:131]
	v_mfma_f32_16x16x32_bf16 v[124:127], v[100:103], v[188:191], v[124:127]
	v_mfma_f32_16x16x32_bf16 v[120:123], v[156:159], v[188:191], v[120:123]
	v_mfma_f32_16x16x32_bf16 v[116:119], v[100:103], v[196:199], v[116:119]
	v_mfma_f32_16x16x32_bf16 v[112:115], v[156:159], v[196:199], v[112:115]
	v_mfma_f32_16x16x32_bf16 v[108:111], v[100:103], v[204:207], v[108:111]
	v_mfma_f32_16x16x32_bf16 v[104:107], v[156:159], v[204:207], v[104:107]
	v_mfma_f32_16x16x32_bf16 v[60:63], v[164:167], v[180:183], v[60:63]
	v_mfma_f32_16x16x32_bf16 v[56:59], v[172:175], v[180:183], v[56:59]
	v_mfma_f32_16x16x32_bf16 v[52:55], v[164:167], v[188:191], v[52:55]
	v_mfma_f32_16x16x32_bf16 v[48:51], v[172:175], v[188:191], v[48:51]
	v_mfma_f32_16x16x32_bf16 v[44:47], v[164:167], v[196:199], v[44:47]
	v_mfma_f32_16x16x32_bf16 v[40:43], v[172:175], v[196:199], v[40:43]
	v_mfma_f32_16x16x32_bf16 v[36:39], v[164:167], v[204:207], v[36:39]
	v_mfma_f32_16x16x32_bf16 v[32:35], v[172:175], v[204:207], v[32:35]
	s_setprio 0
	s_barrier
	s_add_i32 s18, s74, s30
	v_lshl_add_u64 v[208:209], v[208:209], 0, s[12:13]
	s_mov_b32 m0, s18
	ds_read_b128 v[176:179], v235 offset:49152
	ds_read_b128 v[180:183], v235 offset:50176
	ds_read_b128 v[184:187], v235 offset:51200
	ds_read_b128 v[188:191], v235 offset:52224
	ds_read_b128 v[192:195], v235 offset:53248
	ds_read_b128 v[196:199], v235 offset:54272
	ds_read_b128 v[200:203], v235 offset:55296
	ds_read_b128 v[204:207], v235 offset:56320
	global_load_lds_dwordx4 v[208:209], off
	s_add_i32 m0, s18, 0x2000
	s_add_u32 s18, s22, 0xb0080
	v_lshl_add_u64 v[208:209], v[210:211], 0, s[12:13]
	s_addc_u32 s19, s23, 0
	s_add_i32 s22, s75, s30
	global_load_lds_dwordx4 v[208:209], off
	v_lshl_add_u64 v[208:209], s[18:19], 0, v[138:139]
	s_mov_b32 m0, s22
	s_nop 0
	global_load_lds_dwordx4 v[208:209], off
	v_lshl_add_u64 v[208:209], s[18:19], 0, v[142:143]
	s_add_i32 m0, s22, 0x2000
	s_nop 0
	global_load_lds_dwordx4 v[208:209], off
	v_lshl_add_u64 v[208:209], v[212:213], 0, s[12:13]
	s_mov_b32 m0, s55
	s_nop 0
	global_load_lds_dwordx4 v[208:209], off
	v_lshl_add_u64 v[208:209], v[214:215], 0, s[12:13]
	s_mov_b32 m0, s56
	s_nop 0
	global_load_lds_dwordx4 v[208:209], off
	s_setprio 1
	s_waitcnt lgkmcnt(0)
	v_mfma_f32_16x16x32_bf16 v[92:95], v[96:99], v[176:179], v[92:95]
	s_waitcnt vmcnt(8)
	s_waitcnt lgkmcnt(0)
	s_barrier
	v_mfma_f32_16x16x32_bf16 v[88:91], v[152:155], v[176:179], v[88:91]
	v_mfma_f32_16x16x32_bf16 v[84:87], v[96:99], v[184:187], v[84:87]
	v_mfma_f32_16x16x32_bf16 v[80:83], v[152:155], v[184:187], v[80:83]
	v_mfma_f32_16x16x32_bf16 v[76:79], v[96:99], v[192:195], v[76:79]
	v_mfma_f32_16x16x32_bf16 v[72:75], v[152:155], v[192:195], v[72:75]
	v_mfma_f32_16x16x32_bf16 v[68:71], v[96:99], v[200:203], v[68:71]
	v_mfma_f32_16x16x32_bf16 v[64:67], v[152:155], v[200:203], v[64:67]
	v_mfma_f32_16x16x32_bf16 v[28:31], v[160:163], v[176:179], v[28:31]
	v_mfma_f32_16x16x32_bf16 v[24:27], v[168:171], v[176:179], v[24:27]
	v_mfma_f32_16x16x32_bf16 v[20:23], v[160:163], v[184:187], v[20:23]
	v_mfma_f32_16x16x32_bf16 v[16:19], v[168:171], v[184:187], v[16:19]
	v_mfma_f32_16x16x32_bf16 v[12:15], v[160:163], v[192:195], v[12:15]
	v_mfma_f32_16x16x32_bf16 v[8:11], v[168:171], v[192:195], v[8:11]
	v_mfma_f32_16x16x32_bf16 v[4:7], v[160:163], v[200:203], v[4:7]
	v_mfma_f32_16x16x32_bf16 v[0:3], v[168:171], v[200:203], v[0:3]
	v_mfma_f32_16x16x32_bf16 v[92:95], v[100:103], v[180:183], v[92:95]
	v_mfma_f32_16x16x32_bf16 v[88:91], v[156:159], v[180:183], v[88:91]
	v_mfma_f32_16x16x32_bf16 v[84:87], v[100:103], v[188:191], v[84:87]
	v_mfma_f32_16x16x32_bf16 v[80:83], v[156:159], v[188:191], v[80:83]
	v_mfma_f32_16x16x32_bf16 v[76:79], v[100:103], v[196:199], v[76:79]
	v_mfma_f32_16x16x32_bf16 v[72:75], v[156:159], v[196:199], v[72:75]
	v_mfma_f32_16x16x32_bf16 v[68:71], v[100:103], v[204:207], v[68:71]
	v_mfma_f32_16x16x32_bf16 v[64:67], v[156:159], v[204:207], v[64:67]
	v_mfma_f32_16x16x32_bf16 v[28:31], v[164:167], v[180:183], v[28:31]
	v_mfma_f32_16x16x32_bf16 v[24:27], v[172:175], v[180:183], v[24:27]
	v_mfma_f32_16x16x32_bf16 v[20:23], v[164:167], v[188:191], v[20:23]
	v_mfma_f32_16x16x32_bf16 v[16:19], v[172:175], v[188:191], v[16:19]
	v_mfma_f32_16x16x32_bf16 v[12:15], v[164:167], v[196:199], v[12:15]
	v_mfma_f32_16x16x32_bf16 v[8:11], v[172:175], v[196:199], v[8:11]
	v_mfma_f32_16x16x32_bf16 v[4:7], v[164:167], v[204:207], v[4:7]
	v_mfma_f32_16x16x32_bf16 v[0:3], v[172:175], v[204:207], v[0:3]
	s_setprio 0
	s_add_i32 s73, s73, 2
	s_add_u32 s67, s67, 0x100
	s_addc_u32 s72, s72, 0
	s_cmp_gt_u32 s73, 41
	s_mov_b64 s[18:19], s[20:21]
	s_barrier
	s_cbranch_scc0 .LBB0_358
	s_and_b64 vcc, exec, s[14:15]
	s_cbranch_vccz .LBB0_361
	s_barrier

.LBB0_442:
	ds_read_b128 v[128:131], v181
	ds_read_b128 v[132:135], v181 offset:1024
	ds_read_b128 v[136:139], v181 offset:2048
	ds_read_b128 v[140:143], v181 offset:3072
	ds_read_b128 v[160:163], v182
	ds_read_b128 v[164:167], v182 offset:1024
	ds_read_b128 v[168:171], v182 offset:2048
	ds_read_b128 v[172:175], v182 offset:3072
	s_add_u32 s30, s28, 0xfffc0080
	s_addc_u32 s31, s29, -1
	s_cmp_eq_u32 s72, 12
	s_cselect_b32 s35, s21, s31
	s_cselect_b32 s34, s64, s30
	s_cselect_b32 s31, s19, s67
	s_cselect_b32 s30, s65, s66
	v_lshl_add_u64 v[176:177], s[28:29], 0, v[154:155]
	s_add_i32 m0, s42, 0xc000
	ds_read_b128 v[186:189], v183
	ds_read_b128 v[190:193], v183 offset:1024
	ds_read_b128 v[194:197], v183 offset:2048
	ds_read_b128 v[198:201], v183 offset:3072
	ds_read_b128 v[202:205], v183 offset:4096
	ds_read_b128 v[206:209], v183 offset:5120
	ds_read_b128 v[210:213], v183 offset:6144
	ds_read_b128 v[214:217], v183 offset:7168
	global_load_lds_dwordx4 v[176:177], off
	v_lshl_add_u64 v[176:177], s[28:29], 0, v[152:153]
	s_add_i32 m0, s42, 0xe000
	s_nop 0
	global_load_lds_dwordx4 v[176:177], off
	s_setprio 1
	s_waitcnt lgkmcnt(0)
	v_mfma_f32_16x16x32_bf16 v[124:127], v[128:131], v[186:189], v[124:127]
	s_waitcnt vmcnt(8)
	s_waitcnt lgkmcnt(0)
	s_barrier
	v_mfma_f32_16x16x32_bf16 v[120:123], v[136:139], v[186:189], v[120:123]
	v_mfma_f32_16x16x32_bf16 v[108:111], v[128:131], v[194:197], v[108:111]
	v_mfma_f32_16x16x32_bf16 v[104:107], v[136:139], v[194:197], v[104:107]
	v_mfma_f32_16x16x32_bf16 v[92:95], v[128:131], v[202:205], v[92:95]
	v_mfma_f32_16x16x32_bf16 v[88:91], v[136:139], v[202:205], v[88:91]
	v_mfma_f32_16x16x32_bf16 v[76:79], v[128:131], v[210:213], v[76:79]
	v_mfma_f32_16x16x32_bf16 v[72:75], v[136:139], v[210:213], v[72:75]
	v_mfma_f32_16x16x32_bf16 v[116:119], v[160:163], v[186:189], v[116:119]
	v_mfma_f32_16x16x32_bf16 v[112:115], v[168:171], v[186:189], v[112:115]
	v_mfma_f32_16x16x32_bf16 v[100:103], v[160:163], v[194:197], v[100:103]
	v_mfma_f32_16x16x32_bf16 v[96:99], v[168:171], v[194:197], v[96:99]
	v_mfma_f32_16x16x32_bf16 v[84:87], v[160:163], v[202:205], v[84:87]
	v_mfma_f32_16x16x32_bf16 v[80:83], v[168:171], v[202:205], v[80:83]
	v_mfma_f32_16x16x32_bf16 v[68:71], v[160:163], v[210:213], v[68:71]
	v_mfma_f32_16x16x32_bf16 v[64:67], v[168:171], v[210:213], v[64:67]
	v_mfma_f32_16x16x32_bf16 v[124:127], v[132:135], v[190:193], v[124:127]
	v_mfma_f32_16x16x32_bf16 v[120:123], v[140:143], v[190:193], v[120:123]
	v_mfma_f32_16x16x32_bf16 v[108:111], v[132:135], v[198:201], v[108:111]
	v_mfma_f32_16x16x32_bf16 v[104:107], v[140:143], v[198:201], v[104:107]
	v_mfma_f32_16x16x32_bf16 v[92:95], v[132:135], v[206:209], v[92:95]
	v_mfma_f32_16x16x32_bf16 v[88:91], v[140:143], v[206:209], v[88:91]
	v_mfma_f32_16x16x32_bf16 v[76:79], v[132:135], v[214:217], v[76:79]
	v_mfma_f32_16x16x32_bf16 v[72:75], v[140:143], v[214:217], v[72:75]
	v_mfma_f32_16x16x32_bf16 v[116:119], v[164:167], v[190:193], v[116:119]
	v_mfma_f32_16x16x32_bf16 v[112:115], v[172:175], v[190:193], v[112:115]
	v_mfma_f32_16x16x32_bf16 v[100:103], v[164:167], v[198:201], v[100:103]
	v_mfma_f32_16x16x32_bf16 v[96:99], v[172:175], v[198:201], v[96:99]
	v_mfma_f32_16x16x32_bf16 v[84:87], v[164:167], v[206:209], v[84:87]
	v_mfma_f32_16x16x32_bf16 v[80:83], v[172:175], v[206:209], v[80:83]
	v_mfma_f32_16x16x32_bf16 v[68:71], v[164:167], v[214:217], v[68:71]
	v_mfma_f32_16x16x32_bf16 v[64:67], v[172:175], v[214:217], v[64:67]
	s_setprio 0
	s_barrier
	s_add_i32 s73, s61, s41
	v_lshl_add_u64 v[176:177], s[30:31], 0, v[146:147]
	s_mov_b32 m0, s73
	ds_read_b128 v[186:189], v183 offset:16384
	ds_read_b128 v[190:193], v183 offset:17408
	ds_read_b128 v[194:197], v183 offset:18432
	ds_read_b128 v[198:201], v183 offset:19456
	ds_read_b128 v[202:205], v183 offset:20480
	ds_read_b128 v[206:209], v183 offset:21504
	ds_read_b128 v[210:213], v183 offset:22528
	ds_read_b128 v[214:217], v183 offset:23552
	global_load_lds_dwordx4 v[176:177], off
	s_add_i32 m0, s73, 0x2000
	s_add_u32 s74, s30, 0x40000
	v_lshl_add_u64 v[218:219], s[30:31], 0, v[150:151]
	s_addc_u32 s75, s31, 0
	s_add_i32 s73, s62, s41
	global_load_lds_dwordx4 v[218:219], off
	v_lshl_add_u64 v[220:221], s[74:75], 0, v[146:147]
	s_mov_b32 m0, s73
	v_lshl_add_u64 v[222:223], s[34:35], 0, v[148:149]
	global_load_lds_dwordx4 v[220:221], off
	v_lshl_add_u64 v[220:221], s[74:75], 0, v[150:151]
	s_add_i32 m0, s73, 0x2000
	s_nop 0
	global_load_lds_dwordx4 v[220:221], off
	v_lshl_add_u64 v[220:221], s[34:35], 0, v[144:145]
	s_mov_b32 m0, s42
	s_nop 0
	global_load_lds_dwordx4 v[220:221], off
	s_mov_b32 m0, s43
	s_nop 0
	global_load_lds_dwordx4 v[222:223], off
	s_setprio 1
	s_waitcnt lgkmcnt(0)
	v_mfma_f32_16x16x32_bf16 v[60:63], v[128:131], v[186:189], v[60:63]
	s_waitcnt vmcnt(8)
	s_waitcnt lgkmcnt(0)
	s_barrier
	v_mfma_f32_16x16x32_bf16 v[56:59], v[136:139], v[186:189], v[56:59]
	v_mfma_f32_16x16x32_bf16 v[44:47], v[128:131], v[194:197], v[44:47]
	v_mfma_f32_16x16x32_bf16 v[40:43], v[136:139], v[194:197], v[40:43]
	v_mfma_f32_16x16x32_bf16 v[28:31], v[128:131], v[202:205], v[28:31]
	v_mfma_f32_16x16x32_bf16 v[24:27], v[136:139], v[202:205], v[24:27]
	v_mfma_f32_16x16x32_bf16 v[12:15], v[128:131], v[210:213], v[12:15]
	v_mfma_f32_16x16x32_bf16 v[8:11], v[136:139], v[210:213], v[8:11]
	v_mfma_f32_16x16x32_bf16 v[52:55], v[160:163], v[186:189], v[52:55]
	v_mfma_f32_16x16x32_bf16 v[48:51], v[168:171], v[186:189], v[48:51]
	v_mfma_f32_16x16x32_bf16 v[36:39], v[160:163], v[194:197], v[36:39]
	v_mfma_f32_16x16x32_bf16 v[32:35], v[168:171], v[194:197], v[32:35]
	v_mfma_f32_16x16x32_bf16 v[20:23], v[160:163], v[202:205], v[20:23]
	v_mfma_f32_16x16x32_bf16 v[16:19], v[168:171], v[202:205], v[16:19]
	v_mfma_f32_16x16x32_bf16 v[4:7], v[160:163], v[210:213], v[4:7]
	v_mfma_f32_16x16x32_bf16 v[0:3], v[168:171], v[210:213], v[0:3]
	v_mfma_f32_16x16x32_bf16 v[60:63], v[132:135], v[190:193], v[60:63]
	v_mfma_f32_16x16x32_bf16 v[56:59], v[140:143], v[190:193], v[56:59]
	v_mfma_f32_16x16x32_bf16 v[44:47], v[132:135], v[198:201], v[44:47]
	v_mfma_f32_16x16x32_bf16 v[40:43], v[140:143], v[198:201], v[40:43]
	v_mfma_f32_16x16x32_bf16 v[28:31], v[132:135], v[206:209], v[28:31]
	v_mfma_f32_16x16x32_bf16 v[24:27], v[140:143], v[206:209], v[24:27]
	v_mfma_f32_16x16x32_bf16 v[12:15], v[132:135], v[214:217], v[12:15]
	v_mfma_f32_16x16x32_bf16 v[8:11], v[140:143], v[214:217], v[8:11]
	v_mfma_f32_16x16x32_bf16 v[52:55], v[164:167], v[190:193], v[52:55]
	v_mfma_f32_16x16x32_bf16 v[48:51], v[172:175], v[190:193], v[48:51]
	v_mfma_f32_16x16x32_bf16 v[36:39], v[164:167], v[198:201], v[36:39]
	v_mfma_f32_16x16x32_bf16 v[32:35], v[172:175], v[198:201], v[32:35]
	v_mfma_f32_16x16x32_bf16 v[20:23], v[164:167], v[206:209], v[20:23]
	v_mfma_f32_16x16x32_bf16 v[16:19], v[172:175], v[206:209], v[16:19]
	v_mfma_f32_16x16x32_bf16 v[4:7], v[164:167], v[214:217], v[4:7]
	v_mfma_f32_16x16x32_bf16 v[0:3], v[172:175], v[214:217], v[0:3]
	s_setprio 0
	s_barrier
	s_add_i32 s73, 0, 0x18000
	s_add_i32 s74, 0, 0x1c000
	v_add_u32_e32 v140, s73, v180
	v_add_u32_e32 v172, s74, v180
	ds_read_b128 v[128:131], v140
	ds_read_b128 v[132:135], v140 offset:1024
	ds_read_b128 v[136:139], v140 offset:2048
	ds_read_b128 v[140:143], v140 offset:3072
	ds_read_b128 v[160:163], v172
	ds_read_b128 v[164:167], v172 offset:1024
	ds_read_b128 v[168:171], v172 offset:2048
	ds_read_b128 v[172:175], v172 offset:3072
	s_add_u32 s34, s34, 0x40000
	s_addc_u32 s35, s35, 0
	s_mov_b32 m0, s44
	v_lshl_add_u64 v[224:225], s[34:35], 0, v[144:145]
	ds_read_b128 v[186:189], v183 offset:32768
	ds_read_b128 v[190:193], v183 offset:33792
	ds_read_b128 v[194:197], v183 offset:34816
	ds_read_b128 v[198:201], v183 offset:35840
	ds_read_b128 v[202:205], v183 offset:36864
	ds_read_b128 v[206:209], v183 offset:37888
	ds_read_b128 v[210:213], v183 offset:38912
	ds_read_b128 v[214:217], v183 offset:39936
	global_load_lds_dwordx4 v[224:225], off
	v_lshl_add_u64 v[224:225], s[34:35], 0, v[148:149]
	s_mov_b32 m0, s45
	s_nop 0
	global_load_lds_dwordx4 v[224:225], off
	s_setprio 1
	s_waitcnt lgkmcnt(0)
	v_mfma_f32_16x16x32_bf16 v[124:127], v[128:131], v[186:189], v[124:127]
	s_waitcnt vmcnt(8)
	s_waitcnt lgkmcnt(0)
	s_barrier
	v_mfma_f32_16x16x32_bf16 v[120:123], v[136:139], v[186:189], v[120:123]
	v_mfma_f32_16x16x32_bf16 v[108:111], v[128:131], v[194:197], v[108:111]
	v_mfma_f32_16x16x32_bf16 v[104:107], v[136:139], v[194:197], v[104:107]
	v_mfma_f32_16x16x32_bf16 v[92:95], v[128:131], v[202:205], v[92:95]
	v_mfma_f32_16x16x32_bf16 v[88:91], v[136:139], v[202:205], v[88:91]
	v_mfma_f32_16x16x32_bf16 v[76:79], v[128:131], v[210:213], v[76:79]
	v_mfma_f32_16x16x32_bf16 v[72:75], v[136:139], v[210:213], v[72:75]
	v_mfma_f32_16x16x32_bf16 v[116:119], v[160:163], v[186:189], v[116:119]
	v_mfma_f32_16x16x32_bf16 v[112:115], v[168:171], v[186:189], v[112:115]
	v_mfma_f32_16x16x32_bf16 v[100:103], v[160:163], v[194:197], v[100:103]
	v_mfma_f32_16x16x32_bf16 v[96:99], v[168:171], v[194:197], v[96:99]
	v_mfma_f32_16x16x32_bf16 v[84:87], v[160:163], v[202:205], v[84:87]
	v_mfma_f32_16x16x32_bf16 v[80:83], v[168:171], v[202:205], v[80:83]
	v_mfma_f32_16x16x32_bf16 v[68:71], v[160:163], v[210:213], v[68:71]
	v_mfma_f32_16x16x32_bf16 v[64:67], v[168:171], v[210:213], v[64:67]
	v_mfma_f32_16x16x32_bf16 v[124:127], v[132:135], v[190:193], v[124:127]
	v_mfma_f32_16x16x32_bf16 v[120:123], v[140:143], v[190:193], v[120:123]
	v_mfma_f32_16x16x32_bf16 v[108:111], v[132:135], v[198:201], v[108:111]
	v_mfma_f32_16x16x32_bf16 v[104:107], v[140:143], v[198:201], v[104:107]
	v_mfma_f32_16x16x32_bf16 v[92:95], v[132:135], v[206:209], v[92:95]
	v_mfma_f32_16x16x32_bf16 v[88:91], v[140:143], v[206:209], v[88:91]
	v_mfma_f32_16x16x32_bf16 v[76:79], v[132:135], v[214:217], v[76:79]
	v_mfma_f32_16x16x32_bf16 v[72:75], v[140:143], v[214:217], v[72:75]
	v_mfma_f32_16x16x32_bf16 v[116:119], v[164:167], v[190:193], v[116:119]
	v_mfma_f32_16x16x32_bf16 v[112:115], v[172:175], v[190:193], v[112:115]
	v_mfma_f32_16x16x32_bf16 v[100:103], v[164:167], v[198:201], v[100:103]
	v_mfma_f32_16x16x32_bf16 v[96:99], v[172:175], v[198:201], v[96:99]
	v_mfma_f32_16x16x32_bf16 v[84:87], v[164:167], v[206:209], v[84:87]
	v_mfma_f32_16x16x32_bf16 v[80:83], v[172:175], v[206:209], v[80:83]
	v_mfma_f32_16x16x32_bf16 v[68:71], v[164:167], v[214:217], v[68:71]
	v_mfma_f32_16x16x32_bf16 v[64:67], v[172:175], v[214:217], v[64:67]
	s_setprio 0
	s_barrier
	s_add_i32 s34, s73, s41
	v_lshl_add_u64 v[176:177], v[176:177], 0, s[10:11]
	s_mov_b32 m0, s34
	ds_read_b128 v[186:189], v183 offset:49152
	ds_read_b128 v[190:193], v183 offset:50176
	ds_read_b128 v[194:197], v183 offset:51200
	ds_read_b128 v[198:201], v183 offset:52224
	ds_read_b128 v[202:205], v183 offset:53248
	ds_read_b128 v[206:209], v183 offset:54272
	ds_read_b128 v[210:213], v183 offset:55296
	ds_read_b128 v[214:217], v183 offset:56320
	global_load_lds_dwordx4 v[176:177], off
	s_add_i32 m0, s34, 0x2000
	s_add_u32 s30, s30, 0x40080
	v_lshl_add_u64 v[176:177], v[218:219], 0, s[10:11]
	s_addc_u32 s31, s31, 0
	s_add_i32 s34, s74, s41
	global_load_lds_dwordx4 v[176:177], off
	v_lshl_add_u64 v[176:177], s[30:31], 0, v[146:147]
	s_mov_b32 m0, s34
	s_nop 0
	global_load_lds_dwordx4 v[176:177], off
	v_lshl_add_u64 v[176:177], s[30:31], 0, v[150:151]
	s_add_i32 m0, s34, 0x2000
	s_nop 0
	global_load_lds_dwordx4 v[176:177], off
	v_lshl_add_u64 v[176:177], v[220:221], 0, s[10:11]
	s_mov_b32 m0, s58
	s_nop 0
	global_load_lds_dwordx4 v[176:177], off
	v_lshl_add_u64 v[176:177], v[222:223], 0, s[10:11]
	s_mov_b32 m0, s59
	s_nop 0
	global_load_lds_dwordx4 v[176:177], off
	s_setprio 1
	s_waitcnt lgkmcnt(0)
	v_mfma_f32_16x16x32_bf16 v[60:63], v[128:131], v[186:189], v[60:63]
	s_waitcnt vmcnt(8)
	s_waitcnt lgkmcnt(0)
	s_barrier
	v_mfma_f32_16x16x32_bf16 v[56:59], v[136:139], v[186:189], v[56:59]
	v_mfma_f32_16x16x32_bf16 v[44:47], v[128:131], v[194:197], v[44:47]
	v_mfma_f32_16x16x32_bf16 v[40:43], v[136:139], v[194:197], v[40:43]
	v_mfma_f32_16x16x32_bf16 v[28:31], v[128:131], v[202:205], v[28:31]
	v_mfma_f32_16x16x32_bf16 v[24:27], v[136:139], v[202:205], v[24:27]
	v_mfma_f32_16x16x32_bf16 v[12:15], v[128:131], v[210:213], v[12:15]
	v_mfma_f32_16x16x32_bf16 v[8:11], v[136:139], v[210:213], v[8:11]
	v_mfma_f32_16x16x32_bf16 v[52:55], v[160:163], v[186:189], v[52:55]
	v_mfma_f32_16x16x32_bf16 v[48:51], v[168:171], v[186:189], v[48:51]
	v_mfma_f32_16x16x32_bf16 v[36:39], v[160:163], v[194:197], v[36:39]
	v_mfma_f32_16x16x32_bf16 v[32:35], v[168:171], v[194:197], v[32:35]
	v_mfma_f32_16x16x32_bf16 v[20:23], v[160:163], v[202:205], v[20:23]
	v_mfma_f32_16x16x32_bf16 v[16:19], v[168:171], v[202:205], v[16:19]
	v_mfma_f32_16x16x32_bf16 v[4:7], v[160:163], v[210:213], v[4:7]
	v_mfma_f32_16x16x32_bf16 v[0:3], v[168:171], v[210:213], v[0:3]
	v_mfma_f32_16x16x32_bf16 v[60:63], v[132:135], v[190:193], v[60:63]
	v_mfma_f32_16x16x32_bf16 v[56:59], v[140:143], v[190:193], v[56:59]
	v_mfma_f32_16x16x32_bf16 v[44:47], v[132:135], v[198:201], v[44:47]
	v_mfma_f32_16x16x32_bf16 v[40:43], v[140:143], v[198:201], v[40:43]
	v_mfma_f32_16x16x32_bf16 v[28:31], v[132:135], v[206:209], v[28:31]
	v_mfma_f32_16x16x32_bf16 v[24:27], v[140:143], v[206:209], v[24:27]
	v_mfma_f32_16x16x32_bf16 v[12:15], v[132:135], v[214:217], v[12:15]
	v_mfma_f32_16x16x32_bf16 v[8:11], v[140:143], v[214:217], v[8:11]
	v_mfma_f32_16x16x32_bf16 v[52:55], v[164:167], v[190:193], v[52:55]
	v_mfma_f32_16x16x32_bf16 v[48:51], v[172:175], v[190:193], v[48:51]
	v_mfma_f32_16x16x32_bf16 v[36:39], v[164:167], v[198:201], v[36:39]
	v_mfma_f32_16x16x32_bf16 v[32:35], v[172:175], v[198:201], v[32:35]
	v_mfma_f32_16x16x32_bf16 v[20:23], v[164:167], v[206:209], v[20:23]
	v_mfma_f32_16x16x32_bf16 v[16:19], v[172:175], v[206:209], v[16:19]
	v_mfma_f32_16x16x32_bf16 v[4:7], v[164:167], v[214:217], v[4:7]
	v_mfma_f32_16x16x32_bf16 v[0:3], v[172:175], v[214:217], v[0:3]
	s_setprio 0
	s_add_i32 s72, s72, 2
	s_add_u32 s66, s66, 0x100
	s_addc_u32 s67, s67, 0
	s_add_u32 s28, s28, 0x100
	s_addc_u32 s29, s29, 0
	s_cmp_gt_u32 s72, 13
	s_barrier
	s_cbranch_scc0 .LBB0_442
	s_and_b64 vcc, exec, s[12:13]
	s_cbranch_vccz .LBB0_445
	s_barrier

.LBB0_760:
	ds_read_b128 v[144:147], v151
	ds_read_b128 v[154:157], v151 offset:1024
	ds_read_b128 v[158:161], v151 offset:2048
	ds_read_b128 v[162:165], v151 offset:3072
	ds_read_b128 v[166:169], v152
	ds_read_b128 v[170:173], v152 offset:1024
	ds_read_b128 v[174:177], v152 offset:2048
	ds_read_b128 v[178:181], v152 offset:3072
	s_add_u32 s26, s24, 0xfffe0080
	s_addc_u32 s27, s25, -1
	s_cmp_eq_u32 s56, 4
	s_cselect_b32 s29, s17, s27
	s_cselect_b32 s28, s52, s26
	s_cselect_b32 s27, s15, s55
	s_cselect_b32 s26, s53, s54
	v_lshl_add_u64 v[214:215], s[24:25], 0, v[138:139]
	s_add_i32 m0, s23, 0xc000
	ds_read_b128 v[182:185], v153
	ds_read_b128 v[186:189], v153 offset:1024
	ds_read_b128 v[190:193], v153 offset:2048
	ds_read_b128 v[194:197], v153 offset:3072
	ds_read_b128 v[198:201], v153 offset:4096
	ds_read_b128 v[202:205], v153 offset:5120
	ds_read_b128 v[206:209], v153 offset:6144
	ds_read_b128 v[210:213], v153 offset:7168
	global_load_lds_dwordx4 v[214:215], off
	v_lshl_add_u64 v[214:215], s[24:25], 0, v[136:137]
	s_add_i32 m0, s23, 0xe000
	s_nop 0
	global_load_lds_dwordx4 v[214:215], off
	s_setprio 1
	s_waitcnt lgkmcnt(0)
	v_mfma_f32_16x16x32_bf16 v[124:127], v[144:147], v[182:185], v[124:127]
	s_waitcnt vmcnt(8)
	s_waitcnt lgkmcnt(0)
	s_barrier
	v_mfma_f32_16x16x32_bf16 v[120:123], v[158:161], v[182:185], v[120:123]
	v_mfma_f32_16x16x32_bf16 v[108:111], v[144:147], v[190:193], v[108:111]
	v_mfma_f32_16x16x32_bf16 v[104:107], v[158:161], v[190:193], v[104:107]
	v_mfma_f32_16x16x32_bf16 v[92:95], v[144:147], v[198:201], v[92:95]
	v_mfma_f32_16x16x32_bf16 v[88:91], v[158:161], v[198:201], v[88:91]
	v_mfma_f32_16x16x32_bf16 v[76:79], v[144:147], v[206:209], v[76:79]
	v_mfma_f32_16x16x32_bf16 v[72:75], v[158:161], v[206:209], v[72:75]
	v_mfma_f32_16x16x32_bf16 v[116:119], v[166:169], v[182:185], v[116:119]
	v_mfma_f32_16x16x32_bf16 v[112:115], v[174:177], v[182:185], v[112:115]
	v_mfma_f32_16x16x32_bf16 v[100:103], v[166:169], v[190:193], v[100:103]
	v_mfma_f32_16x16x32_bf16 v[96:99], v[174:177], v[190:193], v[96:99]
	v_mfma_f32_16x16x32_bf16 v[84:87], v[166:169], v[198:201], v[84:87]
	v_mfma_f32_16x16x32_bf16 v[80:83], v[174:177], v[198:201], v[80:83]
	v_mfma_f32_16x16x32_bf16 v[68:71], v[166:169], v[206:209], v[68:71]
	v_mfma_f32_16x16x32_bf16 v[64:67], v[174:177], v[206:209], v[64:67]
	v_mfma_f32_16x16x32_bf16 v[124:127], v[154:157], v[186:189], v[124:127]
	v_mfma_f32_16x16x32_bf16 v[120:123], v[162:165], v[186:189], v[120:123]
	v_mfma_f32_16x16x32_bf16 v[108:111], v[154:157], v[194:197], v[108:111]
	v_mfma_f32_16x16x32_bf16 v[104:107], v[162:165], v[194:197], v[104:107]
	v_mfma_f32_16x16x32_bf16 v[92:95], v[154:157], v[202:205], v[92:95]
	v_mfma_f32_16x16x32_bf16 v[88:91], v[162:165], v[202:205], v[88:91]
	v_mfma_f32_16x16x32_bf16 v[76:79], v[154:157], v[210:213], v[76:79]
	v_mfma_f32_16x16x32_bf16 v[72:75], v[162:165], v[210:213], v[72:75]
	v_mfma_f32_16x16x32_bf16 v[116:119], v[170:173], v[186:189], v[116:119]
	v_mfma_f32_16x16x32_bf16 v[112:115], v[178:181], v[186:189], v[112:115]
	v_mfma_f32_16x16x32_bf16 v[100:103], v[170:173], v[194:197], v[100:103]
	v_mfma_f32_16x16x32_bf16 v[96:99], v[178:181], v[194:197], v[96:99]
	v_mfma_f32_16x16x32_bf16 v[84:87], v[170:173], v[202:205], v[84:87]
	v_mfma_f32_16x16x32_bf16 v[80:83], v[178:181], v[202:205], v[80:83]
	v_mfma_f32_16x16x32_bf16 v[68:71], v[170:173], v[210:213], v[68:71]
	v_mfma_f32_16x16x32_bf16 v[64:67], v[178:181], v[210:213], v[64:67]
	s_setprio 0
	s_barrier
	s_add_i32 s57, s49, s39
	v_lshl_add_u64 v[214:215], s[26:27], 0, v[130:131]
	s_mov_b32 m0, s57
	ds_read_b128 v[182:185], v153 offset:16384
	ds_read_b128 v[186:189], v153 offset:17408
	ds_read_b128 v[190:193], v153 offset:18432
	ds_read_b128 v[194:197], v153 offset:19456
	ds_read_b128 v[198:201], v153 offset:20480
	ds_read_b128 v[202:205], v153 offset:21504
	ds_read_b128 v[206:209], v153 offset:22528
	ds_read_b128 v[210:213], v153 offset:23552
	global_load_lds_dwordx4 v[214:215], off
	s_add_i32 m0, s57, 0x2000
	s_add_u32 s58, s26, 0x20000
	v_lshl_add_u64 v[216:217], s[26:27], 0, v[134:135]
	s_addc_u32 s59, s27, 0
	s_add_i32 s57, s50, s39
	global_load_lds_dwordx4 v[216:217], off
	v_lshl_add_u64 v[218:219], s[58:59], 0, v[130:131]
	s_mov_b32 m0, s57
	v_lshl_add_u64 v[220:221], s[28:29], 0, v[132:133]
	global_load_lds_dwordx4 v[218:219], off
	v_lshl_add_u64 v[218:219], s[58:59], 0, v[134:135]
	s_add_i32 m0, s57, 0x2000
	s_nop 0
	global_load_lds_dwordx4 v[218:219], off
	v_lshl_add_u64 v[218:219], s[28:29], 0, v[128:129]
	s_mov_b32 m0, s23
	s_nop 0
	global_load_lds_dwordx4 v[218:219], off
	s_mov_b32 m0, s40
	s_nop 0
	global_load_lds_dwordx4 v[220:221], off
	s_setprio 1
	s_waitcnt lgkmcnt(0)
	v_mfma_f32_16x16x32_bf16 v[60:63], v[144:147], v[182:185], v[60:63]
	s_waitcnt vmcnt(8)
	s_waitcnt lgkmcnt(0)
	s_barrier
	v_mfma_f32_16x16x32_bf16 v[56:59], v[158:161], v[182:185], v[56:59]
	v_mfma_f32_16x16x32_bf16 v[44:47], v[144:147], v[190:193], v[44:47]
	v_mfma_f32_16x16x32_bf16 v[40:43], v[158:161], v[190:193], v[40:43]
	v_mfma_f32_16x16x32_bf16 v[28:31], v[144:147], v[198:201], v[28:31]
	v_mfma_f32_16x16x32_bf16 v[24:27], v[158:161], v[198:201], v[24:27]
	v_mfma_f32_16x16x32_bf16 v[12:15], v[144:147], v[206:209], v[12:15]
	v_mfma_f32_16x16x32_bf16 v[8:11], v[158:161], v[206:209], v[8:11]
	v_mfma_f32_16x16x32_bf16 v[52:55], v[166:169], v[182:185], v[52:55]
	v_mfma_f32_16x16x32_bf16 v[48:51], v[174:177], v[182:185], v[48:51]
	v_mfma_f32_16x16x32_bf16 v[36:39], v[166:169], v[190:193], v[36:39]
	v_mfma_f32_16x16x32_bf16 v[32:35], v[174:177], v[190:193], v[32:35]
	v_mfma_f32_16x16x32_bf16 v[20:23], v[166:169], v[198:201], v[20:23]
	v_mfma_f32_16x16x32_bf16 v[16:19], v[174:177], v[198:201], v[16:19]
	v_mfma_f32_16x16x32_bf16 v[4:7], v[166:169], v[206:209], v[4:7]
	v_mfma_f32_16x16x32_bf16 v[0:3], v[174:177], v[206:209], v[0:3]
	v_mfma_f32_16x16x32_bf16 v[60:63], v[154:157], v[186:189], v[60:63]
	v_mfma_f32_16x16x32_bf16 v[56:59], v[162:165], v[186:189], v[56:59]
	v_mfma_f32_16x16x32_bf16 v[44:47], v[154:157], v[194:197], v[44:47]
	v_mfma_f32_16x16x32_bf16 v[40:43], v[162:165], v[194:197], v[40:43]
	v_mfma_f32_16x16x32_bf16 v[28:31], v[154:157], v[202:205], v[28:31]
	v_mfma_f32_16x16x32_bf16 v[24:27], v[162:165], v[202:205], v[24:27]
	v_mfma_f32_16x16x32_bf16 v[12:15], v[154:157], v[210:213], v[12:15]
	v_mfma_f32_16x16x32_bf16 v[8:11], v[162:165], v[210:213], v[8:11]
	v_mfma_f32_16x16x32_bf16 v[52:55], v[170:173], v[186:189], v[52:55]
	v_mfma_f32_16x16x32_bf16 v[48:51], v[178:181], v[186:189], v[48:51]
	v_mfma_f32_16x16x32_bf16 v[36:39], v[170:173], v[194:197], v[36:39]
	v_mfma_f32_16x16x32_bf16 v[32:35], v[178:181], v[194:197], v[32:35]
	v_mfma_f32_16x16x32_bf16 v[20:23], v[170:173], v[202:205], v[20:23]
	v_mfma_f32_16x16x32_bf16 v[16:19], v[178:181], v[202:205], v[16:19]
	v_mfma_f32_16x16x32_bf16 v[4:7], v[170:173], v[210:213], v[4:7]
	v_mfma_f32_16x16x32_bf16 v[0:3], v[178:181], v[210:213], v[0:3]
	s_setprio 0
	s_barrier
	s_add_i32 s57, 0, 0x18000
	s_add_i32 s58, 0, 0x1c000
	v_add_u32_e32 v162, s57, v150
	v_add_u32_e32 v178, s58, v150
	ds_read_b128 v[144:147], v162
	ds_read_b128 v[154:157], v162 offset:1024
	ds_read_b128 v[158:161], v162 offset:2048
	ds_read_b128 v[162:165], v162 offset:3072
	ds_read_b128 v[166:169], v178
	ds_read_b128 v[170:173], v178 offset:1024
	ds_read_b128 v[174:177], v178 offset:2048
	ds_read_b128 v[178:181], v178 offset:3072
	s_add_u32 s28, s28, 0x20000
	s_addc_u32 s29, s29, 0
	s_mov_b32 m0, s41
	v_lshl_add_u64 v[222:223], s[28:29], 0, v[128:129]
	ds_read_b128 v[182:185], v153 offset:32768
	ds_read_b128 v[186:189], v153 offset:33792
	ds_read_b128 v[190:193], v153 offset:34816
	ds_read_b128 v[194:197], v153 offset:35840
	ds_read_b128 v[198:201], v153 offset:36864
	ds_read_b128 v[202:205], v153 offset:37888
	ds_read_b128 v[206:209], v153 offset:38912
	ds_read_b128 v[210:213], v153 offset:39936
	global_load_lds_dwordx4 v[222:223], off
	v_lshl_add_u64 v[222:223], s[28:29], 0, v[132:133]
	s_mov_b32 m0, s42
	s_nop 0
	global_load_lds_dwordx4 v[222:223], off
	s_setprio 1
	s_waitcnt lgkmcnt(0)
	v_mfma_f32_16x16x32_bf16 v[124:127], v[144:147], v[182:185], v[124:127]
	s_waitcnt vmcnt(8)
	s_waitcnt lgkmcnt(0)
	s_barrier
	v_mfma_f32_16x16x32_bf16 v[120:123], v[158:161], v[182:185], v[120:123]
	v_mfma_f32_16x16x32_bf16 v[108:111], v[144:147], v[190:193], v[108:111]
	v_mfma_f32_16x16x32_bf16 v[104:107], v[158:161], v[190:193], v[104:107]
	v_mfma_f32_16x16x32_bf16 v[92:95], v[144:147], v[198:201], v[92:95]
	v_mfma_f32_16x16x32_bf16 v[88:91], v[158:161], v[198:201], v[88:91]
	v_mfma_f32_16x16x32_bf16 v[76:79], v[144:147], v[206:209], v[76:79]
	v_mfma_f32_16x16x32_bf16 v[72:75], v[158:161], v[206:209], v[72:75]
	v_mfma_f32_16x16x32_bf16 v[116:119], v[166:169], v[182:185], v[116:119]
	v_mfma_f32_16x16x32_bf16 v[112:115], v[174:177], v[182:185], v[112:115]
	v_mfma_f32_16x16x32_bf16 v[100:103], v[166:169], v[190:193], v[100:103]
	v_mfma_f32_16x16x32_bf16 v[96:99], v[174:177], v[190:193], v[96:99]
	v_mfma_f32_16x16x32_bf16 v[84:87], v[166:169], v[198:201], v[84:87]
	v_mfma_f32_16x16x32_bf16 v[80:83], v[174:177], v[198:201], v[80:83]
	v_mfma_f32_16x16x32_bf16 v[68:71], v[166:169], v[206:209], v[68:71]
	v_mfma_f32_16x16x32_bf16 v[64:67], v[174:177], v[206:209], v[64:67]
	v_mfma_f32_16x16x32_bf16 v[124:127], v[154:157], v[186:189], v[124:127]
	v_mfma_f32_16x16x32_bf16 v[120:123], v[162:165], v[186:189], v[120:123]
	v_mfma_f32_16x16x32_bf16 v[108:111], v[154:157], v[194:197], v[108:111]
	v_mfma_f32_16x16x32_bf16 v[104:107], v[162:165], v[194:197], v[104:107]
	v_mfma_f32_16x16x32_bf16 v[92:95], v[154:157], v[202:205], v[92:95]
	v_mfma_f32_16x16x32_bf16 v[88:91], v[162:165], v[202:205], v[88:91]
	v_mfma_f32_16x16x32_bf16 v[76:79], v[154:157], v[210:213], v[76:79]
	v_mfma_f32_16x16x32_bf16 v[72:75], v[162:165], v[210:213], v[72:75]
	v_mfma_f32_16x16x32_bf16 v[116:119], v[170:173], v[186:189], v[116:119]
	v_mfma_f32_16x16x32_bf16 v[112:115], v[178:181], v[186:189], v[112:115]
	v_mfma_f32_16x16x32_bf16 v[100:103], v[170:173], v[194:197], v[100:103]
	v_mfma_f32_16x16x32_bf16 v[96:99], v[178:181], v[194:197], v[96:99]
	v_mfma_f32_16x16x32_bf16 v[84:87], v[170:173], v[202:205], v[84:87]
	v_mfma_f32_16x16x32_bf16 v[80:83], v[178:181], v[202:205], v[80:83]
	v_mfma_f32_16x16x32_bf16 v[68:71], v[170:173], v[210:213], v[68:71]
	v_mfma_f32_16x16x32_bf16 v[64:67], v[178:181], v[210:213], v[64:67]
	s_setprio 0
	s_barrier
	s_add_i32 s28, s57, s39
	v_lshl_add_u64 v[214:215], v[214:215], 0, s[10:11]
	s_mov_b32 m0, s28
	ds_read_b128 v[182:185], v153 offset:49152
	ds_read_b128 v[186:189], v153 offset:50176
	ds_read_b128 v[190:193], v153 offset:51200
	ds_read_b128 v[194:197], v153 offset:52224
	ds_read_b128 v[198:201], v153 offset:53248
	ds_read_b128 v[202:205], v153 offset:54272
	ds_read_b128 v[206:209], v153 offset:55296
	ds_read_b128 v[210:213], v153 offset:56320
	global_load_lds_dwordx4 v[214:215], off
	s_add_i32 m0, s28, 0x2000
	s_add_u32 s26, s26, 0x20080
	v_lshl_add_u64 v[214:215], v[216:217], 0, s[10:11]
	s_addc_u32 s27, s27, 0
	s_add_i32 s28, s58, s39
	global_load_lds_dwordx4 v[214:215], off
	v_lshl_add_u64 v[214:215], s[26:27], 0, v[130:131]
	s_mov_b32 m0, s28
	s_nop 0
	global_load_lds_dwordx4 v[214:215], off
	v_lshl_add_u64 v[214:215], s[26:27], 0, v[134:135]
	s_add_i32 m0, s28, 0x2000
	s_nop 0
	global_load_lds_dwordx4 v[214:215], off
	v_lshl_add_u64 v[214:215], v[218:219], 0, s[10:11]
	s_mov_b32 m0, s46
	s_nop 0
	global_load_lds_dwordx4 v[214:215], off
	v_lshl_add_u64 v[214:215], v[220:221], 0, s[10:11]
	s_mov_b32 m0, s47
	s_nop 0
	global_load_lds_dwordx4 v[214:215], off
	s_setprio 1
	s_waitcnt lgkmcnt(0)
	v_mfma_f32_16x16x32_bf16 v[60:63], v[144:147], v[182:185], v[60:63]
	s_waitcnt vmcnt(8)
	s_waitcnt lgkmcnt(0)
	s_barrier
	v_mfma_f32_16x16x32_bf16 v[56:59], v[158:161], v[182:185], v[56:59]
	v_mfma_f32_16x16x32_bf16 v[44:47], v[144:147], v[190:193], v[44:47]
	v_mfma_f32_16x16x32_bf16 v[40:43], v[158:161], v[190:193], v[40:43]
	v_mfma_f32_16x16x32_bf16 v[28:31], v[144:147], v[198:201], v[28:31]
	v_mfma_f32_16x16x32_bf16 v[24:27], v[158:161], v[198:201], v[24:27]
	v_mfma_f32_16x16x32_bf16 v[12:15], v[144:147], v[206:209], v[12:15]
	v_mfma_f32_16x16x32_bf16 v[8:11], v[158:161], v[206:209], v[8:11]
	v_mfma_f32_16x16x32_bf16 v[52:55], v[166:169], v[182:185], v[52:55]
	v_mfma_f32_16x16x32_bf16 v[48:51], v[174:177], v[182:185], v[48:51]
	v_mfma_f32_16x16x32_bf16 v[36:39], v[166:169], v[190:193], v[36:39]
	v_mfma_f32_16x16x32_bf16 v[32:35], v[174:177], v[190:193], v[32:35]
	v_mfma_f32_16x16x32_bf16 v[20:23], v[166:169], v[198:201], v[20:23]
	v_mfma_f32_16x16x32_bf16 v[16:19], v[174:177], v[198:201], v[16:19]
	v_mfma_f32_16x16x32_bf16 v[4:7], v[166:169], v[206:209], v[4:7]
	v_mfma_f32_16x16x32_bf16 v[0:3], v[174:177], v[206:209], v[0:3]
	v_mfma_f32_16x16x32_bf16 v[60:63], v[154:157], v[186:189], v[60:63]
	v_mfma_f32_16x16x32_bf16 v[56:59], v[162:165], v[186:189], v[56:59]
	v_mfma_f32_16x16x32_bf16 v[44:47], v[154:157], v[194:197], v[44:47]
	v_mfma_f32_16x16x32_bf16 v[40:43], v[162:165], v[194:197], v[40:43]
	v_mfma_f32_16x16x32_bf16 v[28:31], v[154:157], v[202:205], v[28:31]
	v_mfma_f32_16x16x32_bf16 v[24:27], v[162:165], v[202:205], v[24:27]
	v_mfma_f32_16x16x32_bf16 v[12:15], v[154:157], v[210:213], v[12:15]
	v_mfma_f32_16x16x32_bf16 v[8:11], v[162:165], v[210:213], v[8:11]
	v_mfma_f32_16x16x32_bf16 v[52:55], v[170:173], v[186:189], v[52:55]
	v_mfma_f32_16x16x32_bf16 v[48:51], v[178:181], v[186:189], v[48:51]
	v_mfma_f32_16x16x32_bf16 v[36:39], v[170:173], v[194:197], v[36:39]
	v_mfma_f32_16x16x32_bf16 v[32:35], v[178:181], v[194:197], v[32:35]
	v_mfma_f32_16x16x32_bf16 v[20:23], v[170:173], v[202:205], v[20:23]
	v_mfma_f32_16x16x32_bf16 v[16:19], v[178:181], v[202:205], v[16:19]
	v_mfma_f32_16x16x32_bf16 v[4:7], v[170:173], v[210:213], v[4:7]
	v_mfma_f32_16x16x32_bf16 v[0:3], v[178:181], v[210:213], v[0:3]
	s_setprio 0
	s_add_i32 s56, s56, 2
	s_add_u32 s54, s54, 0x100
	s_addc_u32 s55, s55, 0
	s_add_u32 s24, s24, 0x100
	s_addc_u32 s25, s25, 0
	s_cmp_gt_u32 s56, 5
	s_barrier
	s_cbranch_scc0 .LBB0_760
	s_and_b64 vcc, exec, s[12:13]
	s_cbranch_vccz .LBB0_763
	s_barrier

.LBB0_784:
	ds_read_b128 v[144:147], v153
	ds_read_b128 v[156:159], v153 offset:1024
	ds_read_b128 v[160:163], v153 offset:2048
	ds_read_b128 v[164:167], v153 offset:3072
	ds_read_b128 v[168:171], v154
	ds_read_b128 v[172:175], v154 offset:1024
	ds_read_b128 v[176:179], v154 offset:2048
	ds_read_b128 v[180:183], v154 offset:3072
	s_add_u32 s26, s24, 0xfffe0080
	s_addc_u32 s27, s25, -1
	s_cmp_eq_u32 s56, 4
	s_cselect_b32 s29, s17, s27
	s_cselect_b32 s28, s52, s26
	s_cselect_b32 s27, s15, s55
	s_cselect_b32 s26, s53, s54
	v_lshl_add_u64 v[148:149], s[24:25], 0, v[138:139]
	s_add_i32 m0, s23, 0xc000
	ds_read_b128 v[184:187], v155
	ds_read_b128 v[188:191], v155 offset:1024
	ds_read_b128 v[192:195], v155 offset:2048
	ds_read_b128 v[196:199], v155 offset:3072
	ds_read_b128 v[200:203], v155 offset:4096
	ds_read_b128 v[204:207], v155 offset:5120
	ds_read_b128 v[208:211], v155 offset:6144
	ds_read_b128 v[212:215], v155 offset:7168
	global_load_lds_dwordx4 v[148:149], off
	v_lshl_add_u64 v[148:149], s[24:25], 0, v[136:137]
	s_add_i32 m0, s23, 0xe000
	s_nop 0
	global_load_lds_dwordx4 v[148:149], off
	s_setprio 1
	s_waitcnt lgkmcnt(0)
	v_mfma_f32_16x16x32_bf16 v[124:127], v[144:147], v[184:187], v[124:127]
	s_waitcnt vmcnt(8)
	s_waitcnt lgkmcnt(0)
	s_barrier
	v_mfma_f32_16x16x32_bf16 v[120:123], v[160:163], v[184:187], v[120:123]
	v_mfma_f32_16x16x32_bf16 v[108:111], v[144:147], v[192:195], v[108:111]
	v_mfma_f32_16x16x32_bf16 v[104:107], v[160:163], v[192:195], v[104:107]
	v_mfma_f32_16x16x32_bf16 v[92:95], v[144:147], v[200:203], v[92:95]
	v_mfma_f32_16x16x32_bf16 v[88:91], v[160:163], v[200:203], v[88:91]
	v_mfma_f32_16x16x32_bf16 v[76:79], v[144:147], v[208:211], v[76:79]
	v_mfma_f32_16x16x32_bf16 v[72:75], v[160:163], v[208:211], v[72:75]
	v_mfma_f32_16x16x32_bf16 v[116:119], v[168:171], v[184:187], v[116:119]
	v_mfma_f32_16x16x32_bf16 v[112:115], v[176:179], v[184:187], v[112:115]
	v_mfma_f32_16x16x32_bf16 v[100:103], v[168:171], v[192:195], v[100:103]
	v_mfma_f32_16x16x32_bf16 v[96:99], v[176:179], v[192:195], v[96:99]
	v_mfma_f32_16x16x32_bf16 v[84:87], v[168:171], v[200:203], v[84:87]
	v_mfma_f32_16x16x32_bf16 v[80:83], v[176:179], v[200:203], v[80:83]
	v_mfma_f32_16x16x32_bf16 v[68:71], v[168:171], v[208:211], v[68:71]
	v_mfma_f32_16x16x32_bf16 v[64:67], v[176:179], v[208:211], v[64:67]
	v_mfma_f32_16x16x32_bf16 v[124:127], v[156:159], v[188:191], v[124:127]
	v_mfma_f32_16x16x32_bf16 v[120:123], v[164:167], v[188:191], v[120:123]
	v_mfma_f32_16x16x32_bf16 v[108:111], v[156:159], v[196:199], v[108:111]
	v_mfma_f32_16x16x32_bf16 v[104:107], v[164:167], v[196:199], v[104:107]
	v_mfma_f32_16x16x32_bf16 v[92:95], v[156:159], v[204:207], v[92:95]
	v_mfma_f32_16x16x32_bf16 v[88:91], v[164:167], v[204:207], v[88:91]
	v_mfma_f32_16x16x32_bf16 v[76:79], v[156:159], v[212:215], v[76:79]
	v_mfma_f32_16x16x32_bf16 v[72:75], v[164:167], v[212:215], v[72:75]
	v_mfma_f32_16x16x32_bf16 v[116:119], v[172:175], v[188:191], v[116:119]
	v_mfma_f32_16x16x32_bf16 v[112:115], v[180:183], v[188:191], v[112:115]
	v_mfma_f32_16x16x32_bf16 v[100:103], v[172:175], v[196:199], v[100:103]
	v_mfma_f32_16x16x32_bf16 v[96:99], v[180:183], v[196:199], v[96:99]
	v_mfma_f32_16x16x32_bf16 v[84:87], v[172:175], v[204:207], v[84:87]
	v_mfma_f32_16x16x32_bf16 v[80:83], v[180:183], v[204:207], v[80:83]
	v_mfma_f32_16x16x32_bf16 v[68:71], v[172:175], v[212:215], v[68:71]
	v_mfma_f32_16x16x32_bf16 v[64:67], v[180:183], v[212:215], v[64:67]
	s_setprio 0
	s_barrier
	s_add_i32 s57, s49, s39
	v_lshl_add_u64 v[148:149], s[26:27], 0, v[130:131]
	s_mov_b32 m0, s57
	ds_read_b128 v[184:187], v155 offset:16384
	ds_read_b128 v[188:191], v155 offset:17408
	ds_read_b128 v[192:195], v155 offset:18432
	ds_read_b128 v[196:199], v155 offset:19456
	ds_read_b128 v[200:203], v155 offset:20480
	ds_read_b128 v[204:207], v155 offset:21504
	ds_read_b128 v[208:211], v155 offset:22528
	ds_read_b128 v[212:215], v155 offset:23552
	global_load_lds_dwordx4 v[148:149], off
	s_add_i32 m0, s57, 0x2000
	s_add_u32 s58, s26, 0x20000
	v_lshl_add_u64 v[216:217], s[26:27], 0, v[134:135]
	s_addc_u32 s59, s27, 0
	s_add_i32 s57, s50, s39
	global_load_lds_dwordx4 v[216:217], off
	v_lshl_add_u64 v[218:219], s[58:59], 0, v[130:131]
	s_mov_b32 m0, s57
	v_lshl_add_u64 v[220:221], s[28:29], 0, v[132:133]
	global_load_lds_dwordx4 v[218:219], off
	v_lshl_add_u64 v[218:219], s[58:59], 0, v[134:135]
	s_add_i32 m0, s57, 0x2000
	s_nop 0
	global_load_lds_dwordx4 v[218:219], off
	v_lshl_add_u64 v[218:219], s[28:29], 0, v[128:129]
	s_mov_b32 m0, s23
	s_nop 0
	global_load_lds_dwordx4 v[218:219], off
	s_mov_b32 m0, s40
	s_nop 0
	global_load_lds_dwordx4 v[220:221], off
	s_setprio 1
	s_waitcnt lgkmcnt(0)
	v_mfma_f32_16x16x32_bf16 v[60:63], v[144:147], v[184:187], v[60:63]
	s_waitcnt vmcnt(8)
	s_waitcnt lgkmcnt(0)
	s_barrier
	v_mfma_f32_16x16x32_bf16 v[56:59], v[160:163], v[184:187], v[56:59]
	v_mfma_f32_16x16x32_bf16 v[44:47], v[144:147], v[192:195], v[44:47]
	v_mfma_f32_16x16x32_bf16 v[40:43], v[160:163], v[192:195], v[40:43]
	v_mfma_f32_16x16x32_bf16 v[28:31], v[144:147], v[200:203], v[28:31]
	v_mfma_f32_16x16x32_bf16 v[24:27], v[160:163], v[200:203], v[24:27]
	v_mfma_f32_16x16x32_bf16 v[12:15], v[144:147], v[208:211], v[12:15]
	v_mfma_f32_16x16x32_bf16 v[8:11], v[160:163], v[208:211], v[8:11]
	v_mfma_f32_16x16x32_bf16 v[52:55], v[168:171], v[184:187], v[52:55]
	v_mfma_f32_16x16x32_bf16 v[48:51], v[176:179], v[184:187], v[48:51]
	v_mfma_f32_16x16x32_bf16 v[36:39], v[168:171], v[192:195], v[36:39]
	v_mfma_f32_16x16x32_bf16 v[32:35], v[176:179], v[192:195], v[32:35]
	v_mfma_f32_16x16x32_bf16 v[20:23], v[168:171], v[200:203], v[20:23]
	v_mfma_f32_16x16x32_bf16 v[16:19], v[176:179], v[200:203], v[16:19]
	v_mfma_f32_16x16x32_bf16 v[4:7], v[168:171], v[208:211], v[4:7]
	v_mfma_f32_16x16x32_bf16 v[0:3], v[176:179], v[208:211], v[0:3]
	v_mfma_f32_16x16x32_bf16 v[60:63], v[156:159], v[188:191], v[60:63]
	v_mfma_f32_16x16x32_bf16 v[56:59], v[164:167], v[188:191], v[56:59]
	v_mfma_f32_16x16x32_bf16 v[44:47], v[156:159], v[196:199], v[44:47]
	v_mfma_f32_16x16x32_bf16 v[40:43], v[164:167], v[196:199], v[40:43]
	v_mfma_f32_16x16x32_bf16 v[28:31], v[156:159], v[204:207], v[28:31]
	v_mfma_f32_16x16x32_bf16 v[24:27], v[164:167], v[204:207], v[24:27]
	v_mfma_f32_16x16x32_bf16 v[12:15], v[156:159], v[212:215], v[12:15]
	v_mfma_f32_16x16x32_bf16 v[8:11], v[164:167], v[212:215], v[8:11]
	v_mfma_f32_16x16x32_bf16 v[52:55], v[172:175], v[188:191], v[52:55]
	v_mfma_f32_16x16x32_bf16 v[48:51], v[180:183], v[188:191], v[48:51]
	v_mfma_f32_16x16x32_bf16 v[36:39], v[172:175], v[196:199], v[36:39]
	v_mfma_f32_16x16x32_bf16 v[32:35], v[180:183], v[196:199], v[32:35]
	v_mfma_f32_16x16x32_bf16 v[20:23], v[172:175], v[204:207], v[20:23]
	v_mfma_f32_16x16x32_bf16 v[16:19], v[180:183], v[204:207], v[16:19]
	v_mfma_f32_16x16x32_bf16 v[4:7], v[172:175], v[212:215], v[4:7]
	v_mfma_f32_16x16x32_bf16 v[0:3], v[180:183], v[212:215], v[0:3]
	s_setprio 0
	s_barrier
	s_add_i32 s57, 0, 0x18000
	s_add_i32 s58, 0, 0x1c000
	v_add_u32_e32 v164, s57, v152
	v_add_u32_e32 v180, s58, v152
	ds_read_b128 v[144:147], v164
	ds_read_b128 v[156:159], v164 offset:1024
	ds_read_b128 v[160:163], v164 offset:2048
	ds_read_b128 v[164:167], v164 offset:3072
	ds_read_b128 v[168:171], v180
	ds_read_b128 v[172:175], v180 offset:1024
	ds_read_b128 v[176:179], v180 offset:2048
	ds_read_b128 v[180:183], v180 offset:3072
	s_add_u32 s28, s28, 0x20000
	s_addc_u32 s29, s29, 0
	s_mov_b32 m0, s41
	v_lshl_add_u64 v[222:223], s[28:29], 0, v[128:129]
	ds_read_b128 v[184:187], v155 offset:32768
	ds_read_b128 v[188:191], v155 offset:33792
	ds_read_b128 v[192:195], v155 offset:34816
	ds_read_b128 v[196:199], v155 offset:35840
	ds_read_b128 v[200:203], v155 offset:36864
	ds_read_b128 v[204:207], v155 offset:37888
	ds_read_b128 v[208:211], v155 offset:38912
	ds_read_b128 v[212:215], v155 offset:39936
	global_load_lds_dwordx4 v[222:223], off
	v_lshl_add_u64 v[222:223], s[28:29], 0, v[132:133]
	s_mov_b32 m0, s42
	s_nop 0
	global_load_lds_dwordx4 v[222:223], off
	s_setprio 1
	s_waitcnt lgkmcnt(0)
	v_mfma_f32_16x16x32_bf16 v[124:127], v[144:147], v[184:187], v[124:127]
	s_waitcnt vmcnt(8)
	s_waitcnt lgkmcnt(0)
	s_barrier
	v_mfma_f32_16x16x32_bf16 v[120:123], v[160:163], v[184:187], v[120:123]
	v_mfma_f32_16x16x32_bf16 v[108:111], v[144:147], v[192:195], v[108:111]
	v_mfma_f32_16x16x32_bf16 v[104:107], v[160:163], v[192:195], v[104:107]
	v_mfma_f32_16x16x32_bf16 v[92:95], v[144:147], v[200:203], v[92:95]
	v_mfma_f32_16x16x32_bf16 v[88:91], v[160:163], v[200:203], v[88:91]
	v_mfma_f32_16x16x32_bf16 v[76:79], v[144:147], v[208:211], v[76:79]
	v_mfma_f32_16x16x32_bf16 v[72:75], v[160:163], v[208:211], v[72:75]
	v_mfma_f32_16x16x32_bf16 v[116:119], v[168:171], v[184:187], v[116:119]
	v_mfma_f32_16x16x32_bf16 v[112:115], v[176:179], v[184:187], v[112:115]
	v_mfma_f32_16x16x32_bf16 v[100:103], v[168:171], v[192:195], v[100:103]
	v_mfma_f32_16x16x32_bf16 v[96:99], v[176:179], v[192:195], v[96:99]
	v_mfma_f32_16x16x32_bf16 v[84:87], v[168:171], v[200:203], v[84:87]
	v_mfma_f32_16x16x32_bf16 v[80:83], v[176:179], v[200:203], v[80:83]
	v_mfma_f32_16x16x32_bf16 v[68:71], v[168:171], v[208:211], v[68:71]
	v_mfma_f32_16x16x32_bf16 v[64:67], v[176:179], v[208:211], v[64:67]
	v_mfma_f32_16x16x32_bf16 v[124:127], v[156:159], v[188:191], v[124:127]
	v_mfma_f32_16x16x32_bf16 v[120:123], v[164:167], v[188:191], v[120:123]
	v_mfma_f32_16x16x32_bf16 v[108:111], v[156:159], v[196:199], v[108:111]
	v_mfma_f32_16x16x32_bf16 v[104:107], v[164:167], v[196:199], v[104:107]
	v_mfma_f32_16x16x32_bf16 v[92:95], v[156:159], v[204:207], v[92:95]
	v_mfma_f32_16x16x32_bf16 v[88:91], v[164:167], v[204:207], v[88:91]
	v_mfma_f32_16x16x32_bf16 v[76:79], v[156:159], v[212:215], v[76:79]
	v_mfma_f32_16x16x32_bf16 v[72:75], v[164:167], v[212:215], v[72:75]
	v_mfma_f32_16x16x32_bf16 v[116:119], v[172:175], v[188:191], v[116:119]
	v_mfma_f32_16x16x32_bf16 v[112:115], v[180:183], v[188:191], v[112:115]
	v_mfma_f32_16x16x32_bf16 v[100:103], v[172:175], v[196:199], v[100:103]
	v_mfma_f32_16x16x32_bf16 v[96:99], v[180:183], v[196:199], v[96:99]
	v_mfma_f32_16x16x32_bf16 v[84:87], v[172:175], v[204:207], v[84:87]
	v_mfma_f32_16x16x32_bf16 v[80:83], v[180:183], v[204:207], v[80:83]
	v_mfma_f32_16x16x32_bf16 v[68:71], v[172:175], v[212:215], v[68:71]
	v_mfma_f32_16x16x32_bf16 v[64:67], v[180:183], v[212:215], v[64:67]
	s_setprio 0
	s_barrier
	s_add_i32 s28, s57, s39
	v_lshl_add_u64 v[148:149], v[148:149], 0, s[10:11]
	s_mov_b32 m0, s28
	ds_read_b128 v[184:187], v155 offset:49152
	ds_read_b128 v[188:191], v155 offset:50176
	ds_read_b128 v[192:195], v155 offset:51200
	ds_read_b128 v[196:199], v155 offset:52224
	ds_read_b128 v[200:203], v155 offset:53248
	ds_read_b128 v[204:207], v155 offset:54272
	ds_read_b128 v[208:211], v155 offset:55296
	ds_read_b128 v[212:215], v155 offset:56320
	global_load_lds_dwordx4 v[148:149], off
	s_add_i32 m0, s28, 0x2000
	s_add_u32 s26, s26, 0x20080
	v_lshl_add_u64 v[148:149], v[216:217], 0, s[10:11]
	s_addc_u32 s27, s27, 0
	s_add_i32 s28, s58, s39
	global_load_lds_dwordx4 v[148:149], off
	v_lshl_add_u64 v[148:149], s[26:27], 0, v[130:131]
	s_mov_b32 m0, s28
	s_nop 0
	global_load_lds_dwordx4 v[148:149], off
	v_lshl_add_u64 v[148:149], s[26:27], 0, v[134:135]
	s_add_i32 m0, s28, 0x2000
	s_nop 0
	global_load_lds_dwordx4 v[148:149], off
	v_lshl_add_u64 v[148:149], v[218:219], 0, s[10:11]
	s_mov_b32 m0, s46
	s_nop 0
	global_load_lds_dwordx4 v[148:149], off
	v_lshl_add_u64 v[148:149], v[220:221], 0, s[10:11]
	s_mov_b32 m0, s47
	s_nop 0
	global_load_lds_dwordx4 v[148:149], off
	s_setprio 1
	s_waitcnt lgkmcnt(0)
	v_mfma_f32_16x16x32_bf16 v[60:63], v[144:147], v[184:187], v[60:63]
	s_waitcnt vmcnt(8)
	s_waitcnt lgkmcnt(0)
	s_barrier
	v_mfma_f32_16x16x32_bf16 v[56:59], v[160:163], v[184:187], v[56:59]
	v_mfma_f32_16x16x32_bf16 v[44:47], v[144:147], v[192:195], v[44:47]
	v_mfma_f32_16x16x32_bf16 v[40:43], v[160:163], v[192:195], v[40:43]
	v_mfma_f32_16x16x32_bf16 v[28:31], v[144:147], v[200:203], v[28:31]
	v_mfma_f32_16x16x32_bf16 v[24:27], v[160:163], v[200:203], v[24:27]
	v_mfma_f32_16x16x32_bf16 v[12:15], v[144:147], v[208:211], v[12:15]
	v_mfma_f32_16x16x32_bf16 v[8:11], v[160:163], v[208:211], v[8:11]
	v_mfma_f32_16x16x32_bf16 v[52:55], v[168:171], v[184:187], v[52:55]
	v_mfma_f32_16x16x32_bf16 v[48:51], v[176:179], v[184:187], v[48:51]
	v_mfma_f32_16x16x32_bf16 v[36:39], v[168:171], v[192:195], v[36:39]
	v_mfma_f32_16x16x32_bf16 v[32:35], v[176:179], v[192:195], v[32:35]
	v_mfma_f32_16x16x32_bf16 v[20:23], v[168:171], v[200:203], v[20:23]
	v_mfma_f32_16x16x32_bf16 v[16:19], v[176:179], v[200:203], v[16:19]
	v_mfma_f32_16x16x32_bf16 v[4:7], v[168:171], v[208:211], v[4:7]
	v_mfma_f32_16x16x32_bf16 v[0:3], v[176:179], v[208:211], v[0:3]
	v_mfma_f32_16x16x32_bf16 v[60:63], v[156:159], v[188:191], v[60:63]
	v_mfma_f32_16x16x32_bf16 v[56:59], v[164:167], v[188:191], v[56:59]
	v_mfma_f32_16x16x32_bf16 v[44:47], v[156:159], v[196:199], v[44:47]
	v_mfma_f32_16x16x32_bf16 v[40:43], v[164:167], v[196:199], v[40:43]
	v_mfma_f32_16x16x32_bf16 v[28:31], v[156:159], v[204:207], v[28:31]
	v_mfma_f32_16x16x32_bf16 v[24:27], v[164:167], v[204:207], v[24:27]
	v_mfma_f32_16x16x32_bf16 v[12:15], v[156:159], v[212:215], v[12:15]
	v_mfma_f32_16x16x32_bf16 v[8:11], v[164:167], v[212:215], v[8:11]
	v_mfma_f32_16x16x32_bf16 v[52:55], v[172:175], v[188:191], v[52:55]
	v_mfma_f32_16x16x32_bf16 v[48:51], v[180:183], v[188:191], v[48:51]
	v_mfma_f32_16x16x32_bf16 v[36:39], v[172:175], v[196:199], v[36:39]
	v_mfma_f32_16x16x32_bf16 v[32:35], v[180:183], v[196:199], v[32:35]
	v_mfma_f32_16x16x32_bf16 v[20:23], v[172:175], v[204:207], v[20:23]
	v_mfma_f32_16x16x32_bf16 v[16:19], v[180:183], v[204:207], v[16:19]
	v_mfma_f32_16x16x32_bf16 v[4:7], v[172:175], v[212:215], v[4:7]
	v_mfma_f32_16x16x32_bf16 v[0:3], v[180:183], v[212:215], v[0:3]
	s_setprio 0
	s_add_i32 s56, s56, 2
	s_add_u32 s54, s54, 0x100
	s_addc_u32 s55, s55, 0
	s_add_u32 s24, s24, 0x100
	s_addc_u32 s25, s25, 0
	s_cmp_gt_u32 s56, 5
	s_barrier
	s_cbranch_scc0 .LBB0_784
	s_and_b64 vcc, exec, s[12:13]
	s_cbranch_vccz .LBB0_787
	s_barrier

.LBB0_854:
	ds_read_b128 v[128:131], v225
	ds_read_b128 v[132:135], v225 offset:1024
	ds_read_b128 v[136:139], v225 offset:2048
	ds_read_b128 v[140:143], v225 offset:3072
	ds_read_b128 v[160:163], v226
	ds_read_b128 v[164:167], v226 offset:1024
	ds_read_b128 v[168:171], v226 offset:2048
	ds_read_b128 v[172:175], v226 offset:3072
	s_add_u32 s30, s28, 0xfffc0080
	s_addc_u32 s31, s29, -1
	s_cmp_eq_u32 s64, 12
	s_cselect_b32 s35, s19, s31
	s_cselect_b32 s34, s25, s30
	s_cselect_b32 s31, s17, s63
	s_cselect_b32 s30, s27, s62
	v_lshl_add_u64 v[208:209], s[28:29], 0, v[154:155]
	s_add_i32 m0, s43, 0xc000
	ds_read_b128 v[176:179], v227
	ds_read_b128 v[180:183], v227 offset:1024
	ds_read_b128 v[184:187], v227 offset:2048
	ds_read_b128 v[188:191], v227 offset:3072
	ds_read_b128 v[192:195], v227 offset:4096
	ds_read_b128 v[196:199], v227 offset:5120
	ds_read_b128 v[200:203], v227 offset:6144
	ds_read_b128 v[204:207], v227 offset:7168
	global_load_lds_dwordx4 v[208:209], off
	v_lshl_add_u64 v[208:209], s[28:29], 0, v[152:153]
	s_add_i32 m0, s43, 0xe000
	s_nop 0
	global_load_lds_dwordx4 v[208:209], off
	s_setprio 1
	s_waitcnt lgkmcnt(0)
	v_mfma_f32_16x16x32_bf16 v[124:127], v[128:131], v[176:179], v[124:127]
	s_waitcnt vmcnt(8)
	s_waitcnt lgkmcnt(0)
	s_barrier
	v_mfma_f32_16x16x32_bf16 v[120:123], v[136:139], v[176:179], v[120:123]
	v_mfma_f32_16x16x32_bf16 v[116:119], v[128:131], v[184:187], v[116:119]
	v_mfma_f32_16x16x32_bf16 v[112:115], v[136:139], v[184:187], v[112:115]
	v_mfma_f32_16x16x32_bf16 v[108:111], v[128:131], v[192:195], v[108:111]
	v_mfma_f32_16x16x32_bf16 v[104:107], v[136:139], v[192:195], v[104:107]
	v_mfma_f32_16x16x32_bf16 v[100:103], v[128:131], v[200:203], v[100:103]
	v_mfma_f32_16x16x32_bf16 v[96:99], v[136:139], v[200:203], v[96:99]
	v_mfma_f32_16x16x32_bf16 v[60:63], v[160:163], v[176:179], v[60:63]
	v_mfma_f32_16x16x32_bf16 v[56:59], v[168:171], v[176:179], v[56:59]
	v_mfma_f32_16x16x32_bf16 v[52:55], v[160:163], v[184:187], v[52:55]
	v_mfma_f32_16x16x32_bf16 v[48:51], v[168:171], v[184:187], v[48:51]
	v_mfma_f32_16x16x32_bf16 v[44:47], v[160:163], v[192:195], v[44:47]
	v_mfma_f32_16x16x32_bf16 v[40:43], v[168:171], v[192:195], v[40:43]
	v_mfma_f32_16x16x32_bf16 v[36:39], v[160:163], v[200:203], v[36:39]
	v_mfma_f32_16x16x32_bf16 v[32:35], v[168:171], v[200:203], v[32:35]
	v_mfma_f32_16x16x32_bf16 v[124:127], v[132:135], v[180:183], v[124:127]
	v_mfma_f32_16x16x32_bf16 v[120:123], v[140:143], v[180:183], v[120:123]
	v_mfma_f32_16x16x32_bf16 v[116:119], v[132:135], v[188:191], v[116:119]
	v_mfma_f32_16x16x32_bf16 v[112:115], v[140:143], v[188:191], v[112:115]
	v_mfma_f32_16x16x32_bf16 v[108:111], v[132:135], v[196:199], v[108:111]
	v_mfma_f32_16x16x32_bf16 v[104:107], v[140:143], v[196:199], v[104:107]
	v_mfma_f32_16x16x32_bf16 v[100:103], v[132:135], v[204:207], v[100:103]
	v_mfma_f32_16x16x32_bf16 v[96:99], v[140:143], v[204:207], v[96:99]
	v_mfma_f32_16x16x32_bf16 v[60:63], v[164:167], v[180:183], v[60:63]
	v_mfma_f32_16x16x32_bf16 v[56:59], v[172:175], v[180:183], v[56:59]
	v_mfma_f32_16x16x32_bf16 v[52:55], v[164:167], v[188:191], v[52:55]
	v_mfma_f32_16x16x32_bf16 v[48:51], v[172:175], v[188:191], v[48:51]
	v_mfma_f32_16x16x32_bf16 v[44:47], v[164:167], v[196:199], v[44:47]
	v_mfma_f32_16x16x32_bf16 v[40:43], v[172:175], v[196:199], v[40:43]
	v_mfma_f32_16x16x32_bf16 v[36:39], v[164:167], v[204:207], v[36:39]
	v_mfma_f32_16x16x32_bf16 v[32:35], v[172:175], v[204:207], v[32:35]
	s_setprio 0
	s_barrier
	s_add_i32 s65, s60, s42
	v_lshl_add_u64 v[208:209], s[30:31], 0, v[146:147]
	s_mov_b32 m0, s65
	ds_read_b128 v[176:179], v227 offset:16384
	ds_read_b128 v[180:183], v227 offset:17408
	ds_read_b128 v[184:187], v227 offset:18432
	ds_read_b128 v[188:191], v227 offset:19456
	ds_read_b128 v[192:195], v227 offset:20480
	ds_read_b128 v[196:199], v227 offset:21504
	ds_read_b128 v[200:203], v227 offset:22528
	ds_read_b128 v[204:207], v227 offset:23552
	global_load_lds_dwordx4 v[208:209], off
	s_add_i32 m0, s65, 0x2000
	s_add_u32 s66, s30, 0x40000
	v_lshl_add_u64 v[210:211], s[30:31], 0, v[150:151]
	s_addc_u32 s67, s31, 0
	s_add_i32 s65, s61, s42
	global_load_lds_dwordx4 v[210:211], off
	v_lshl_add_u64 v[212:213], s[66:67], 0, v[146:147]
	s_mov_b32 m0, s65
	v_lshl_add_u64 v[214:215], s[34:35], 0, v[148:149]
	global_load_lds_dwordx4 v[212:213], off
	v_lshl_add_u64 v[212:213], s[66:67], 0, v[150:151]
	s_add_i32 m0, s65, 0x2000
	s_nop 0
	global_load_lds_dwordx4 v[212:213], off
	v_lshl_add_u64 v[212:213], s[34:35], 0, v[144:145]
	s_mov_b32 m0, s43
	s_nop 0
	global_load_lds_dwordx4 v[212:213], off
	s_mov_b32 m0, s44
	s_nop 0
	global_load_lds_dwordx4 v[214:215], off
	s_setprio 1
	s_waitcnt lgkmcnt(0)
	v_mfma_f32_16x16x32_bf16 v[92:95], v[128:131], v[176:179], v[92:95]
	s_waitcnt vmcnt(8)
	s_waitcnt lgkmcnt(0)
	s_barrier
	v_mfma_f32_16x16x32_bf16 v[88:91], v[136:139], v[176:179], v[88:91]
	v_mfma_f32_16x16x32_bf16 v[84:87], v[128:131], v[184:187], v[84:87]
	v_mfma_f32_16x16x32_bf16 v[80:83], v[136:139], v[184:187], v[80:83]
	v_mfma_f32_16x16x32_bf16 v[76:79], v[128:131], v[192:195], v[76:79]
	v_mfma_f32_16x16x32_bf16 v[72:75], v[136:139], v[192:195], v[72:75]
	v_mfma_f32_16x16x32_bf16 v[68:71], v[128:131], v[200:203], v[68:71]
	v_mfma_f32_16x16x32_bf16 v[64:67], v[136:139], v[200:203], v[64:67]
	v_mfma_f32_16x16x32_bf16 v[28:31], v[160:163], v[176:179], v[28:31]
	v_mfma_f32_16x16x32_bf16 v[24:27], v[168:171], v[176:179], v[24:27]
	v_mfma_f32_16x16x32_bf16 v[20:23], v[160:163], v[184:187], v[20:23]
	v_mfma_f32_16x16x32_bf16 v[16:19], v[168:171], v[184:187], v[16:19]
	v_mfma_f32_16x16x32_bf16 v[12:15], v[160:163], v[192:195], v[12:15]
	v_mfma_f32_16x16x32_bf16 v[8:11], v[168:171], v[192:195], v[8:11]
	v_mfma_f32_16x16x32_bf16 v[4:7], v[160:163], v[200:203], v[4:7]
	v_mfma_f32_16x16x32_bf16 v[0:3], v[168:171], v[200:203], v[0:3]
	v_mfma_f32_16x16x32_bf16 v[92:95], v[132:135], v[180:183], v[92:95]
	v_mfma_f32_16x16x32_bf16 v[88:91], v[140:143], v[180:183], v[88:91]
	v_mfma_f32_16x16x32_bf16 v[84:87], v[132:135], v[188:191], v[84:87]
	v_mfma_f32_16x16x32_bf16 v[80:83], v[140:143], v[188:191], v[80:83]
	v_mfma_f32_16x16x32_bf16 v[76:79], v[132:135], v[196:199], v[76:79]
	v_mfma_f32_16x16x32_bf16 v[72:75], v[140:143], v[196:199], v[72:75]
	v_mfma_f32_16x16x32_bf16 v[68:71], v[132:135], v[204:207], v[68:71]
	v_mfma_f32_16x16x32_bf16 v[64:67], v[140:143], v[204:207], v[64:67]
	v_mfma_f32_16x16x32_bf16 v[28:31], v[164:167], v[180:183], v[28:31]
	v_mfma_f32_16x16x32_bf16 v[24:27], v[172:175], v[180:183], v[24:27]
	v_mfma_f32_16x16x32_bf16 v[20:23], v[164:167], v[188:191], v[20:23]
	v_mfma_f32_16x16x32_bf16 v[16:19], v[172:175], v[188:191], v[16:19]
	v_mfma_f32_16x16x32_bf16 v[12:15], v[164:167], v[196:199], v[12:15]
	v_mfma_f32_16x16x32_bf16 v[8:11], v[172:175], v[196:199], v[8:11]
	v_mfma_f32_16x16x32_bf16 v[4:7], v[164:167], v[204:207], v[4:7]
	v_mfma_f32_16x16x32_bf16 v[0:3], v[172:175], v[204:207], v[0:3]
	s_setprio 0
	s_barrier
	s_add_i32 s65, 0, 0x18000
	s_add_i32 s66, 0, 0x1c000
	v_add_u32_e32 v140, s65, v224
	v_add_u32_e32 v172, s66, v224
	ds_read_b128 v[128:131], v140
	ds_read_b128 v[132:135], v140 offset:1024
	ds_read_b128 v[136:139], v140 offset:2048
	ds_read_b128 v[140:143], v140 offset:3072
	ds_read_b128 v[160:163], v172
	ds_read_b128 v[164:167], v172 offset:1024
	ds_read_b128 v[168:171], v172 offset:2048
	ds_read_b128 v[172:175], v172 offset:3072
	s_add_u32 s34, s34, 0x40000
	s_addc_u32 s35, s35, 0
	s_mov_b32 m0, s45
	v_lshl_add_u64 v[216:217], s[34:35], 0, v[144:145]
	ds_read_b128 v[176:179], v227 offset:32768
	ds_read_b128 v[180:183], v227 offset:33792
	ds_read_b128 v[184:187], v227 offset:34816
	ds_read_b128 v[188:191], v227 offset:35840
	ds_read_b128 v[192:195], v227 offset:36864
	ds_read_b128 v[196:199], v227 offset:37888
	ds_read_b128 v[200:203], v227 offset:38912
	ds_read_b128 v[204:207], v227 offset:39936
	global_load_lds_dwordx4 v[216:217], off
	v_lshl_add_u64 v[216:217], s[34:35], 0, v[148:149]
	s_mov_b32 m0, s46
	s_nop 0
	global_load_lds_dwordx4 v[216:217], off
	s_setprio 1
	s_waitcnt lgkmcnt(0)
	v_mfma_f32_16x16x32_bf16 v[124:127], v[128:131], v[176:179], v[124:127]
	s_waitcnt vmcnt(8)
	s_waitcnt lgkmcnt(0)
	s_barrier
	v_mfma_f32_16x16x32_bf16 v[120:123], v[136:139], v[176:179], v[120:123]
	v_mfma_f32_16x16x32_bf16 v[116:119], v[128:131], v[184:187], v[116:119]
	v_mfma_f32_16x16x32_bf16 v[112:115], v[136:139], v[184:187], v[112:115]
	v_mfma_f32_16x16x32_bf16 v[108:111], v[128:131], v[192:195], v[108:111]
	v_mfma_f32_16x16x32_bf16 v[104:107], v[136:139], v[192:195], v[104:107]
	v_mfma_f32_16x16x32_bf16 v[100:103], v[128:131], v[200:203], v[100:103]
	v_mfma_f32_16x16x32_bf16 v[96:99], v[136:139], v[200:203], v[96:99]
	v_mfma_f32_16x16x32_bf16 v[60:63], v[160:163], v[176:179], v[60:63]
	v_mfma_f32_16x16x32_bf16 v[56:59], v[168:171], v[176:179], v[56:59]
	v_mfma_f32_16x16x32_bf16 v[52:55], v[160:163], v[184:187], v[52:55]
	v_mfma_f32_16x16x32_bf16 v[48:51], v[168:171], v[184:187], v[48:51]
	v_mfma_f32_16x16x32_bf16 v[44:47], v[160:163], v[192:195], v[44:47]
	v_mfma_f32_16x16x32_bf16 v[40:43], v[168:171], v[192:195], v[40:43]
	v_mfma_f32_16x16x32_bf16 v[36:39], v[160:163], v[200:203], v[36:39]
	v_mfma_f32_16x16x32_bf16 v[32:35], v[168:171], v[200:203], v[32:35]
	v_mfma_f32_16x16x32_bf16 v[124:127], v[132:135], v[180:183], v[124:127]
	v_mfma_f32_16x16x32_bf16 v[120:123], v[140:143], v[180:183], v[120:123]
	v_mfma_f32_16x16x32_bf16 v[116:119], v[132:135], v[188:191], v[116:119]
	v_mfma_f32_16x16x32_bf16 v[112:115], v[140:143], v[188:191], v[112:115]
	v_mfma_f32_16x16x32_bf16 v[108:111], v[132:135], v[196:199], v[108:111]
	v_mfma_f32_16x16x32_bf16 v[104:107], v[140:143], v[196:199], v[104:107]
	v_mfma_f32_16x16x32_bf16 v[100:103], v[132:135], v[204:207], v[100:103]
	v_mfma_f32_16x16x32_bf16 v[96:99], v[140:143], v[204:207], v[96:99]
	v_mfma_f32_16x16x32_bf16 v[60:63], v[164:167], v[180:183], v[60:63]
	v_mfma_f32_16x16x32_bf16 v[56:59], v[172:175], v[180:183], v[56:59]
	v_mfma_f32_16x16x32_bf16 v[52:55], v[164:167], v[188:191], v[52:55]
	v_mfma_f32_16x16x32_bf16 v[48:51], v[172:175], v[188:191], v[48:51]
	v_mfma_f32_16x16x32_bf16 v[44:47], v[164:167], v[196:199], v[44:47]
	v_mfma_f32_16x16x32_bf16 v[40:43], v[172:175], v[196:199], v[40:43]
	v_mfma_f32_16x16x32_bf16 v[36:39], v[164:167], v[204:207], v[36:39]
	v_mfma_f32_16x16x32_bf16 v[32:35], v[172:175], v[204:207], v[32:35]
	s_setprio 0
	s_barrier
	s_add_i32 s34, s65, s42
	v_lshl_add_u64 v[208:209], v[208:209], 0, s[12:13]
	s_mov_b32 m0, s34
	ds_read_b128 v[176:179], v227 offset:49152
	ds_read_b128 v[180:183], v227 offset:50176
	ds_read_b128 v[184:187], v227 offset:51200
	ds_read_b128 v[188:191], v227 offset:52224
	ds_read_b128 v[192:195], v227 offset:53248
	ds_read_b128 v[196:199], v227 offset:54272
	ds_read_b128 v[200:203], v227 offset:55296
	ds_read_b128 v[204:207], v227 offset:56320
	global_load_lds_dwordx4 v[208:209], off
	s_add_i32 m0, s34, 0x2000
	s_add_u32 s30, s30, 0x40080
	v_lshl_add_u64 v[208:209], v[210:211], 0, s[12:13]
	s_addc_u32 s31, s31, 0
	s_add_i32 s34, s66, s42
	global_load_lds_dwordx4 v[208:209], off
	v_lshl_add_u64 v[208:209], s[30:31], 0, v[146:147]
	s_mov_b32 m0, s34
	s_nop 0
	global_load_lds_dwordx4 v[208:209], off
	v_lshl_add_u64 v[208:209], s[30:31], 0, v[150:151]
	s_add_i32 m0, s34, 0x2000
	s_nop 0
	global_load_lds_dwordx4 v[208:209], off
	v_lshl_add_u64 v[208:209], v[212:213], 0, s[12:13]
	s_mov_b32 m0, s54
	s_nop 0
	global_load_lds_dwordx4 v[208:209], off
	v_lshl_add_u64 v[208:209], v[214:215], 0, s[12:13]
	s_mov_b32 m0, s55
	s_nop 0
	global_load_lds_dwordx4 v[208:209], off
	s_setprio 1
	s_waitcnt lgkmcnt(0)
	v_mfma_f32_16x16x32_bf16 v[92:95], v[128:131], v[176:179], v[92:95]
	s_waitcnt vmcnt(8)
	s_waitcnt lgkmcnt(0)
	s_barrier
	v_mfma_f32_16x16x32_bf16 v[88:91], v[136:139], v[176:179], v[88:91]
	v_mfma_f32_16x16x32_bf16 v[84:87], v[128:131], v[184:187], v[84:87]
	v_mfma_f32_16x16x32_bf16 v[80:83], v[136:139], v[184:187], v[80:83]
	v_mfma_f32_16x16x32_bf16 v[76:79], v[128:131], v[192:195], v[76:79]
	v_mfma_f32_16x16x32_bf16 v[72:75], v[136:139], v[192:195], v[72:75]
	v_mfma_f32_16x16x32_bf16 v[68:71], v[128:131], v[200:203], v[68:71]
	v_mfma_f32_16x16x32_bf16 v[64:67], v[136:139], v[200:203], v[64:67]
	v_mfma_f32_16x16x32_bf16 v[28:31], v[160:163], v[176:179], v[28:31]
	v_mfma_f32_16x16x32_bf16 v[24:27], v[168:171], v[176:179], v[24:27]
	v_mfma_f32_16x16x32_bf16 v[20:23], v[160:163], v[184:187], v[20:23]
	v_mfma_f32_16x16x32_bf16 v[16:19], v[168:171], v[184:187], v[16:19]
	v_mfma_f32_16x16x32_bf16 v[12:15], v[160:163], v[192:195], v[12:15]
	v_mfma_f32_16x16x32_bf16 v[8:11], v[168:171], v[192:195], v[8:11]
	v_mfma_f32_16x16x32_bf16 v[4:7], v[160:163], v[200:203], v[4:7]
	v_mfma_f32_16x16x32_bf16 v[0:3], v[168:171], v[200:203], v[0:3]
	v_mfma_f32_16x16x32_bf16 v[92:95], v[132:135], v[180:183], v[92:95]
	v_mfma_f32_16x16x32_bf16 v[88:91], v[140:143], v[180:183], v[88:91]
	v_mfma_f32_16x16x32_bf16 v[84:87], v[132:135], v[188:191], v[84:87]
	v_mfma_f32_16x16x32_bf16 v[80:83], v[140:143], v[188:191], v[80:83]
	v_mfma_f32_16x16x32_bf16 v[76:79], v[132:135], v[196:199], v[76:79]
	v_mfma_f32_16x16x32_bf16 v[72:75], v[140:143], v[196:199], v[72:75]
	v_mfma_f32_16x16x32_bf16 v[68:71], v[132:135], v[204:207], v[68:71]
	v_mfma_f32_16x16x32_bf16 v[64:67], v[140:143], v[204:207], v[64:67]
	v_mfma_f32_16x16x32_bf16 v[28:31], v[164:167], v[180:183], v[28:31]
	v_mfma_f32_16x16x32_bf16 v[24:27], v[172:175], v[180:183], v[24:27]
	v_mfma_f32_16x16x32_bf16 v[20:23], v[164:167], v[188:191], v[20:23]
	v_mfma_f32_16x16x32_bf16 v[16:19], v[172:175], v[188:191], v[16:19]
	v_mfma_f32_16x16x32_bf16 v[12:15], v[164:167], v[196:199], v[12:15]
	v_mfma_f32_16x16x32_bf16 v[8:11], v[172:175], v[196:199], v[8:11]
	v_mfma_f32_16x16x32_bf16 v[4:7], v[164:167], v[204:207], v[4:7]
	v_mfma_f32_16x16x32_bf16 v[0:3], v[172:175], v[204:207], v[0:3]
	s_setprio 0
	s_add_i32 s64, s64, 2
	s_add_u32 s62, s62, 0x100
	s_addc_u32 s63, s63, 0
	s_add_u32 s28, s28, 0x100
	s_addc_u32 s29, s29, 0
	s_cmp_gt_u32 s64, 13
	s_barrier
	s_cbranch_scc0 .LBB0_854
	s_and_b64 vcc, exec, s[14:15]
	s_cbranch_vccz .LBB0_857
	s_barrier

.LBB0_930:
	ds_read_b128 v[128:131], v173
	ds_read_b128 v[132:135], v173 offset:1024
	ds_read_b128 v[152:155], v173 offset:2048
	ds_read_b128 v[158:161], v173 offset:3072
	ds_read_b128 v[164:167], v177
	ds_read_b128 v[180:183], v177 offset:1024
	ds_read_b128 v[186:189], v177 offset:2048
	ds_read_b128 v[190:193], v177 offset:3072
	s_add_u32 s34, s6, 0xfffc0080
	s_addc_u32 s35, s7, -1
	s_cmp_eq_u32 s64, 12
	s_cselect_b32 s37, s27, s35
	s_cselect_b32 s36, s60, s34
	s_cselect_b32 s35, s25, s63
	s_cselect_b32 s34, s61, s62
	v_lshl_add_u64 v[170:171], s[6:7], 0, v[146:147]
	s_add_i32 m0, s43, 0xc000
	ds_read_b128 v[194:197], v179
	ds_read_b128 v[198:201], v179 offset:1024
	ds_read_b128 v[202:205], v179 offset:2048
	ds_read_b128 v[206:209], v179 offset:3072
	ds_read_b128 v[210:213], v179 offset:4096
	ds_read_b128 v[214:217], v179 offset:5120
	ds_read_b128 v[218:221], v179 offset:6144
	ds_read_b128 v[222:225], v179 offset:7168
	global_load_lds_dwordx4 v[170:171], off
	v_lshl_add_u64 v[170:171], s[6:7], 0, v[144:145]
	s_add_i32 m0, s43, 0xe000
	s_nop 0
	global_load_lds_dwordx4 v[170:171], off
	s_setprio 1
	s_waitcnt lgkmcnt(0)
	v_mfma_f32_16x16x32_bf16 v[124:127], v[128:131], v[194:197], v[124:127]
	s_waitcnt vmcnt(8)
	s_waitcnt lgkmcnt(0)
	s_barrier
	v_mfma_f32_16x16x32_bf16 v[116:119], v[152:155], v[194:197], v[116:119]
	v_mfma_f32_16x16x32_bf16 v[108:111], v[128:131], v[202:205], v[108:111]
	v_mfma_f32_16x16x32_bf16 v[100:103], v[152:155], v[202:205], v[100:103]
	v_mfma_f32_16x16x32_bf16 v[92:95], v[128:131], v[210:213], v[92:95]
	v_mfma_f32_16x16x32_bf16 v[84:87], v[152:155], v[210:213], v[84:87]
	v_mfma_f32_16x16x32_bf16 v[76:79], v[128:131], v[218:221], v[76:79]
	v_mfma_f32_16x16x32_bf16 v[68:71], v[152:155], v[218:221], v[68:71]
	v_mfma_f32_16x16x32_bf16 v[120:123], v[164:167], v[194:197], v[120:123]
	v_mfma_f32_16x16x32_bf16 v[112:115], v[186:189], v[194:197], v[112:115]
	v_mfma_f32_16x16x32_bf16 v[104:107], v[164:167], v[202:205], v[104:107]
	v_mfma_f32_16x16x32_bf16 v[96:99], v[186:189], v[202:205], v[96:99]
	v_mfma_f32_16x16x32_bf16 v[88:91], v[164:167], v[210:213], v[88:91]
	v_mfma_f32_16x16x32_bf16 v[80:83], v[186:189], v[210:213], v[80:83]
	v_mfma_f32_16x16x32_bf16 v[72:75], v[164:167], v[218:221], v[72:75]
	v_mfma_f32_16x16x32_bf16 v[64:67], v[186:189], v[218:221], v[64:67]
	v_mfma_f32_16x16x32_bf16 v[124:127], v[132:135], v[198:201], v[124:127]
	v_mfma_f32_16x16x32_bf16 v[116:119], v[158:161], v[198:201], v[116:119]
	v_mfma_f32_16x16x32_bf16 v[108:111], v[132:135], v[206:209], v[108:111]
	v_mfma_f32_16x16x32_bf16 v[100:103], v[158:161], v[206:209], v[100:103]
	v_mfma_f32_16x16x32_bf16 v[92:95], v[132:135], v[214:217], v[92:95]
	v_mfma_f32_16x16x32_bf16 v[84:87], v[158:161], v[214:217], v[84:87]
	v_mfma_f32_16x16x32_bf16 v[76:79], v[132:135], v[222:225], v[76:79]
	v_mfma_f32_16x16x32_bf16 v[68:71], v[158:161], v[222:225], v[68:71]
	v_mfma_f32_16x16x32_bf16 v[120:123], v[180:183], v[198:201], v[120:123]
	v_mfma_f32_16x16x32_bf16 v[112:115], v[190:193], v[198:201], v[112:115]
	v_mfma_f32_16x16x32_bf16 v[104:107], v[180:183], v[206:209], v[104:107]
	v_mfma_f32_16x16x32_bf16 v[96:99], v[190:193], v[206:209], v[96:99]
	v_mfma_f32_16x16x32_bf16 v[88:91], v[180:183], v[214:217], v[88:91]
	v_mfma_f32_16x16x32_bf16 v[80:83], v[190:193], v[214:217], v[80:83]
	v_mfma_f32_16x16x32_bf16 v[72:75], v[180:183], v[222:225], v[72:75]
	v_mfma_f32_16x16x32_bf16 v[64:67], v[190:193], v[222:225], v[64:67]
	s_setprio 0
	s_barrier
	s_add_i32 s65, s56, s40
	v_lshl_add_u64 v[170:171], s[34:35], 0, v[140:141]
	s_mov_b32 m0, s65
	ds_read_b128 v[194:197], v179 offset:16384
	ds_read_b128 v[198:201], v179 offset:17408
	ds_read_b128 v[202:205], v179 offset:18432
	ds_read_b128 v[206:209], v179 offset:19456
	ds_read_b128 v[210:213], v179 offset:20480
	ds_read_b128 v[214:217], v179 offset:21504
	ds_read_b128 v[218:221], v179 offset:22528
	ds_read_b128 v[222:225], v179 offset:23552
	global_load_lds_dwordx4 v[170:171], off
	s_add_i32 m0, s65, 0x2000
	s_add_u32 s66, s34, 0x40000
	v_lshl_add_u64 v[174:175], s[34:35], 0, v[136:137]
	s_addc_u32 s67, s35, 0
	s_add_i32 s65, s57, s40
	global_load_lds_dwordx4 v[174:175], off
	v_lshl_add_u64 v[226:227], s[66:67], 0, v[140:141]
	s_mov_b32 m0, s65
	v_lshl_add_u64 v[228:229], s[36:37], 0, v[138:139]
	global_load_lds_dwordx4 v[226:227], off
	v_lshl_add_u64 v[226:227], s[66:67], 0, v[136:137]
	s_add_i32 m0, s65, 0x2000
	s_nop 0
	global_load_lds_dwordx4 v[226:227], off
	v_lshl_add_u64 v[226:227], s[36:37], 0, v[142:143]
	s_mov_b32 m0, s43
	s_nop 0
	global_load_lds_dwordx4 v[226:227], off
	s_mov_b32 m0, s44
	s_nop 0
	global_load_lds_dwordx4 v[228:229], off
	s_setprio 1
	s_waitcnt lgkmcnt(0)
	v_mfma_f32_16x16x32_bf16 v[60:63], v[128:131], v[194:197], v[60:63]
	s_waitcnt vmcnt(8)
	s_waitcnt lgkmcnt(0)
	s_barrier
	v_mfma_f32_16x16x32_bf16 v[52:55], v[152:155], v[194:197], v[52:55]
	v_mfma_f32_16x16x32_bf16 v[44:47], v[128:131], v[202:205], v[44:47]
	v_mfma_f32_16x16x32_bf16 v[36:39], v[152:155], v[202:205], v[36:39]
	v_mfma_f32_16x16x32_bf16 v[28:31], v[128:131], v[210:213], v[28:31]
	v_mfma_f32_16x16x32_bf16 v[20:23], v[152:155], v[210:213], v[20:23]
	v_mfma_f32_16x16x32_bf16 v[12:15], v[128:131], v[218:221], v[12:15]
	v_mfma_f32_16x16x32_bf16 v[4:7], v[152:155], v[218:221], v[4:7]
	v_mfma_f32_16x16x32_bf16 v[56:59], v[164:167], v[194:197], v[56:59]
	v_mfma_f32_16x16x32_bf16 v[48:51], v[186:189], v[194:197], v[48:51]
	v_mfma_f32_16x16x32_bf16 v[40:43], v[164:167], v[202:205], v[40:43]
	v_mfma_f32_16x16x32_bf16 v[32:35], v[186:189], v[202:205], v[32:35]
	v_mfma_f32_16x16x32_bf16 v[24:27], v[164:167], v[210:213], v[24:27]
	v_mfma_f32_16x16x32_bf16 v[16:19], v[186:189], v[210:213], v[16:19]
	v_mfma_f32_16x16x32_bf16 v[8:11], v[164:167], v[218:221], v[8:11]
	v_mfma_f32_16x16x32_bf16 v[0:3], v[186:189], v[218:221], v[0:3]
	v_mfma_f32_16x16x32_bf16 v[60:63], v[132:135], v[198:201], v[60:63]
	v_mfma_f32_16x16x32_bf16 v[52:55], v[158:161], v[198:201], v[52:55]
	v_mfma_f32_16x16x32_bf16 v[44:47], v[132:135], v[206:209], v[44:47]
	v_mfma_f32_16x16x32_bf16 v[36:39], v[158:161], v[206:209], v[36:39]
	v_mfma_f32_16x16x32_bf16 v[28:31], v[132:135], v[214:217], v[28:31]
	v_mfma_f32_16x16x32_bf16 v[20:23], v[158:161], v[214:217], v[20:23]
	v_mfma_f32_16x16x32_bf16 v[12:15], v[132:135], v[222:225], v[12:15]
	v_mfma_f32_16x16x32_bf16 v[4:7], v[158:161], v[222:225], v[4:7]
	v_mfma_f32_16x16x32_bf16 v[56:59], v[180:183], v[198:201], v[56:59]
	v_mfma_f32_16x16x32_bf16 v[48:51], v[190:193], v[198:201], v[48:51]
	v_mfma_f32_16x16x32_bf16 v[40:43], v[180:183], v[206:209], v[40:43]
	v_mfma_f32_16x16x32_bf16 v[32:35], v[190:193], v[206:209], v[32:35]
	v_mfma_f32_16x16x32_bf16 v[24:27], v[180:183], v[214:217], v[24:27]
	v_mfma_f32_16x16x32_bf16 v[16:19], v[190:193], v[214:217], v[16:19]
	v_mfma_f32_16x16x32_bf16 v[8:11], v[180:183], v[222:225], v[8:11]
	v_mfma_f32_16x16x32_bf16 v[0:3], v[190:193], v[222:225], v[0:3]
	s_setprio 0
	s_barrier
	s_add_i32 s65, 0, 0x18000
	v_add_u32_e32 v156, s65, v169
	s_add_i32 s66, 0, 0x1c000
	ds_read_b128 v[128:131], v156
	ds_read_b128 v[132:135], v156 offset:1024
	ds_read_b128 v[152:155], v156 offset:2048
	ds_read_b128 v[158:161], v156 offset:3072
	v_add_u32_e32 v156, s66, v169
	ds_read_b128 v[164:167], v156
	ds_read_b128 v[180:183], v156 offset:1024
	ds_read_b128 v[186:189], v156 offset:2048
	ds_read_b128 v[190:193], v156 offset:3072
	s_add_u32 s36, s36, 0x40000
	s_addc_u32 s37, s37, 0
	s_mov_b32 m0, s45
	v_lshl_add_u64 v[230:231], s[36:37], 0, v[142:143]
	ds_read_b128 v[194:197], v179 offset:32768
	ds_read_b128 v[198:201], v179 offset:33792
	ds_read_b128 v[202:205], v179 offset:34816
	ds_read_b128 v[206:209], v179 offset:35840
	ds_read_b128 v[210:213], v179 offset:36864
	ds_read_b128 v[214:217], v179 offset:37888
	ds_read_b128 v[218:221], v179 offset:38912
	ds_read_b128 v[222:225], v179 offset:39936
	global_load_lds_dwordx4 v[230:231], off
	v_lshl_add_u64 v[230:231], s[36:37], 0, v[138:139]
	s_mov_b32 m0, s46
	s_nop 0
	global_load_lds_dwordx4 v[230:231], off
	s_setprio 1
	s_waitcnt lgkmcnt(0)
	v_mfma_f32_16x16x32_bf16 v[124:127], v[128:131], v[194:197], v[124:127]
	s_waitcnt vmcnt(8)
	s_waitcnt lgkmcnt(0)
	s_barrier
	v_mfma_f32_16x16x32_bf16 v[116:119], v[152:155], v[194:197], v[116:119]
	v_mfma_f32_16x16x32_bf16 v[108:111], v[128:131], v[202:205], v[108:111]
	v_mfma_f32_16x16x32_bf16 v[100:103], v[152:155], v[202:205], v[100:103]
	v_mfma_f32_16x16x32_bf16 v[92:95], v[128:131], v[210:213], v[92:95]
	v_mfma_f32_16x16x32_bf16 v[84:87], v[152:155], v[210:213], v[84:87]
	v_mfma_f32_16x16x32_bf16 v[76:79], v[128:131], v[218:221], v[76:79]
	v_mfma_f32_16x16x32_bf16 v[68:71], v[152:155], v[218:221], v[68:71]
	v_mfma_f32_16x16x32_bf16 v[120:123], v[164:167], v[194:197], v[120:123]
	v_mfma_f32_16x16x32_bf16 v[112:115], v[186:189], v[194:197], v[112:115]
	v_mfma_f32_16x16x32_bf16 v[104:107], v[164:167], v[202:205], v[104:107]
	v_mfma_f32_16x16x32_bf16 v[96:99], v[186:189], v[202:205], v[96:99]
	v_mfma_f32_16x16x32_bf16 v[88:91], v[164:167], v[210:213], v[88:91]
	v_mfma_f32_16x16x32_bf16 v[80:83], v[186:189], v[210:213], v[80:83]
	v_mfma_f32_16x16x32_bf16 v[72:75], v[164:167], v[218:221], v[72:75]
	v_mfma_f32_16x16x32_bf16 v[64:67], v[186:189], v[218:221], v[64:67]
	v_mfma_f32_16x16x32_bf16 v[124:127], v[132:135], v[198:201], v[124:127]
	v_mfma_f32_16x16x32_bf16 v[116:119], v[158:161], v[198:201], v[116:119]
	v_mfma_f32_16x16x32_bf16 v[108:111], v[132:135], v[206:209], v[108:111]
	v_mfma_f32_16x16x32_bf16 v[100:103], v[158:161], v[206:209], v[100:103]
	v_mfma_f32_16x16x32_bf16 v[92:95], v[132:135], v[214:217], v[92:95]
	v_mfma_f32_16x16x32_bf16 v[84:87], v[158:161], v[214:217], v[84:87]
	v_mfma_f32_16x16x32_bf16 v[76:79], v[132:135], v[222:225], v[76:79]
	v_mfma_f32_16x16x32_bf16 v[68:71], v[158:161], v[222:225], v[68:71]
	v_mfma_f32_16x16x32_bf16 v[120:123], v[180:183], v[198:201], v[120:123]
	v_mfma_f32_16x16x32_bf16 v[112:115], v[190:193], v[198:201], v[112:115]
	v_mfma_f32_16x16x32_bf16 v[104:107], v[180:183], v[206:209], v[104:107]
	v_mfma_f32_16x16x32_bf16 v[96:99], v[190:193], v[206:209], v[96:99]
	v_mfma_f32_16x16x32_bf16 v[88:91], v[180:183], v[214:217], v[88:91]
	v_mfma_f32_16x16x32_bf16 v[80:83], v[190:193], v[214:217], v[80:83]
	v_mfma_f32_16x16x32_bf16 v[72:75], v[180:183], v[222:225], v[72:75]
	v_mfma_f32_16x16x32_bf16 v[64:67], v[190:193], v[222:225], v[64:67]
	s_setprio 0
	s_barrier
	s_add_i32 s36, s65, s40
	v_lshl_add_u64 v[170:171], v[170:171], 0, s[14:15]
	s_mov_b32 m0, s36
	ds_read_b128 v[194:197], v179 offset:49152
	ds_read_b128 v[198:201], v179 offset:50176
	ds_read_b128 v[202:205], v179 offset:51200
	ds_read_b128 v[206:209], v179 offset:52224
	ds_read_b128 v[210:213], v179 offset:53248
	ds_read_b128 v[214:217], v179 offset:54272
	ds_read_b128 v[218:221], v179 offset:55296
	ds_read_b128 v[222:225], v179 offset:56320
	global_load_lds_dwordx4 v[170:171], off
	s_add_i32 m0, s36, 0x2000
	s_add_u32 s34, s34, 0x40080
	v_lshl_add_u64 v[170:171], v[174:175], 0, s[14:15]
	s_addc_u32 s35, s35, 0
	s_add_i32 s36, s66, s40
	global_load_lds_dwordx4 v[170:171], off
	v_lshl_add_u64 v[170:171], s[34:35], 0, v[140:141]
	s_mov_b32 m0, s36
	s_nop 0
	global_load_lds_dwordx4 v[170:171], off
	v_lshl_add_u64 v[170:171], s[34:35], 0, v[136:137]
	s_add_i32 m0, s36, 0x2000
	s_nop 0
	global_load_lds_dwordx4 v[170:171], off
	v_lshl_add_u64 v[170:171], v[226:227], 0, s[14:15]
	s_mov_b32 m0, s53
	s_nop 0
	global_load_lds_dwordx4 v[170:171], off
	v_lshl_add_u64 v[170:171], v[228:229], 0, s[14:15]
	s_mov_b32 m0, s54
	s_nop 0
	global_load_lds_dwordx4 v[170:171], off
	s_setprio 1
	s_waitcnt lgkmcnt(0)
	v_mfma_f32_16x16x32_bf16 v[60:63], v[128:131], v[194:197], v[60:63]
	s_waitcnt vmcnt(8)
	s_waitcnt lgkmcnt(0)
	s_barrier
	v_mfma_f32_16x16x32_bf16 v[52:55], v[152:155], v[194:197], v[52:55]
	v_mfma_f32_16x16x32_bf16 v[44:47], v[128:131], v[202:205], v[44:47]
	v_mfma_f32_16x16x32_bf16 v[36:39], v[152:155], v[202:205], v[36:39]
	v_mfma_f32_16x16x32_bf16 v[28:31], v[128:131], v[210:213], v[28:31]
	v_mfma_f32_16x16x32_bf16 v[20:23], v[152:155], v[210:213], v[20:23]
	v_mfma_f32_16x16x32_bf16 v[12:15], v[128:131], v[218:221], v[12:15]
	v_mfma_f32_16x16x32_bf16 v[4:7], v[152:155], v[218:221], v[4:7]
	v_mfma_f32_16x16x32_bf16 v[56:59], v[164:167], v[194:197], v[56:59]
	v_mfma_f32_16x16x32_bf16 v[48:51], v[186:189], v[194:197], v[48:51]
	v_mfma_f32_16x16x32_bf16 v[40:43], v[164:167], v[202:205], v[40:43]
	v_mfma_f32_16x16x32_bf16 v[32:35], v[186:189], v[202:205], v[32:35]
	v_mfma_f32_16x16x32_bf16 v[24:27], v[164:167], v[210:213], v[24:27]
	v_mfma_f32_16x16x32_bf16 v[16:19], v[186:189], v[210:213], v[16:19]
	v_mfma_f32_16x16x32_bf16 v[8:11], v[164:167], v[218:221], v[8:11]
	v_mfma_f32_16x16x32_bf16 v[0:3], v[186:189], v[218:221], v[0:3]
	v_mfma_f32_16x16x32_bf16 v[60:63], v[132:135], v[198:201], v[60:63]
	v_mfma_f32_16x16x32_bf16 v[52:55], v[158:161], v[198:201], v[52:55]
	v_mfma_f32_16x16x32_bf16 v[44:47], v[132:135], v[206:209], v[44:47]
	v_mfma_f32_16x16x32_bf16 v[36:39], v[158:161], v[206:209], v[36:39]
	v_mfma_f32_16x16x32_bf16 v[28:31], v[132:135], v[214:217], v[28:31]
	v_mfma_f32_16x16x32_bf16 v[20:23], v[158:161], v[214:217], v[20:23]
	v_mfma_f32_16x16x32_bf16 v[12:15], v[132:135], v[222:225], v[12:15]
	v_mfma_f32_16x16x32_bf16 v[4:7], v[158:161], v[222:225], v[4:7]
	v_mfma_f32_16x16x32_bf16 v[56:59], v[180:183], v[198:201], v[56:59]
	v_mfma_f32_16x16x32_bf16 v[48:51], v[190:193], v[198:201], v[48:51]
	v_mfma_f32_16x16x32_bf16 v[40:43], v[180:183], v[206:209], v[40:43]
	v_mfma_f32_16x16x32_bf16 v[32:35], v[190:193], v[206:209], v[32:35]
	v_mfma_f32_16x16x32_bf16 v[24:27], v[180:183], v[214:217], v[24:27]
	v_mfma_f32_16x16x32_bf16 v[16:19], v[190:193], v[214:217], v[16:19]
	v_mfma_f32_16x16x32_bf16 v[8:11], v[180:183], v[222:225], v[8:11]
	v_mfma_f32_16x16x32_bf16 v[0:3], v[190:193], v[222:225], v[0:3]
	s_setprio 0
	s_add_i32 s64, s64, 2
	s_add_u32 s62, s62, 0x100
	s_addc_u32 s63, s63, 0
	s_add_u32 s6, s6, 0x100
	s_addc_u32 s7, s7, 0
	s_cmp_gt_u32 s64, 13
	s_barrier
	s_cbranch_scc0 .LBB0_930
	s_and_b64 vcc, exec, s[16:17]
	s_cbranch_vccz .LBB0_933
	s_barrier

.LBB0_1002:
	ds_read_b128 v[144:147], v171
	ds_read_b128 v[148:151], v171 offset:1024
	ds_read_b128 v[152:155], v171 offset:2048
	ds_read_b128 v[156:159], v171 offset:3072
	ds_read_b128 v[160:163], v172
	ds_read_b128 v[164:167], v172 offset:1024
	ds_read_b128 v[174:177], v172 offset:2048
	ds_read_b128 v[178:181], v172 offset:3072
	s_add_u32 s16, s14, 0x100
	s_addc_u32 s17, s15, 0
	s_cmp_eq_u32 s50, 40
	s_cselect_b32 s21, s3, s17
	s_cselect_b32 s20, s2, s16
	s_cselect_b32 s19, s13, s49
	s_cselect_b32 s18, s12, s48
	v_lshl_add_u64 v[214:215], s[14:15], 0, v[138:139]
	s_add_i32 m0, s28, 0xc000
	ds_read_b128 v[182:185], v173
	ds_read_b128 v[186:189], v173 offset:1024
	ds_read_b128 v[190:193], v173 offset:2048
	ds_read_b128 v[194:197], v173 offset:3072
	ds_read_b128 v[198:201], v173 offset:4096
	ds_read_b128 v[202:205], v173 offset:5120
	ds_read_b128 v[206:209], v173 offset:6144
	ds_read_b128 v[210:213], v173 offset:7168
	global_load_lds_dwordx4 v[214:215], off
	v_lshl_add_u64 v[214:215], s[14:15], 0, v[136:137]
	s_add_i32 m0, s28, 0xe000
	s_nop 0
	global_load_lds_dwordx4 v[214:215], off
	s_setprio 1
	s_waitcnt lgkmcnt(0)
	v_mfma_f32_16x16x32_bf16 v[124:127], v[144:147], v[182:185], v[124:127]
	s_waitcnt vmcnt(8)
	s_waitcnt lgkmcnt(0)
	s_barrier
	v_mfma_f32_16x16x32_bf16 v[120:123], v[152:155], v[182:185], v[120:123]
	v_mfma_f32_16x16x32_bf16 v[116:119], v[144:147], v[190:193], v[116:119]
	v_mfma_f32_16x16x32_bf16 v[112:115], v[152:155], v[190:193], v[112:115]
	v_mfma_f32_16x16x32_bf16 v[108:111], v[144:147], v[198:201], v[108:111]
	v_mfma_f32_16x16x32_bf16 v[104:107], v[152:155], v[198:201], v[104:107]
	v_mfma_f32_16x16x32_bf16 v[100:103], v[144:147], v[206:209], v[100:103]
	v_mfma_f32_16x16x32_bf16 v[96:99], v[152:155], v[206:209], v[96:99]
	v_mfma_f32_16x16x32_bf16 v[60:63], v[160:163], v[182:185], v[60:63]
	v_mfma_f32_16x16x32_bf16 v[56:59], v[174:177], v[182:185], v[56:59]
	v_mfma_f32_16x16x32_bf16 v[52:55], v[160:163], v[190:193], v[52:55]
	v_mfma_f32_16x16x32_bf16 v[48:51], v[174:177], v[190:193], v[48:51]
	v_mfma_f32_16x16x32_bf16 v[44:47], v[160:163], v[198:201], v[44:47]
	v_mfma_f32_16x16x32_bf16 v[40:43], v[174:177], v[198:201], v[40:43]
	v_mfma_f32_16x16x32_bf16 v[36:39], v[160:163], v[206:209], v[36:39]
	v_mfma_f32_16x16x32_bf16 v[32:35], v[174:177], v[206:209], v[32:35]
	v_mfma_f32_16x16x32_bf16 v[124:127], v[148:151], v[186:189], v[124:127]
	v_mfma_f32_16x16x32_bf16 v[120:123], v[156:159], v[186:189], v[120:123]
	v_mfma_f32_16x16x32_bf16 v[116:119], v[148:151], v[194:197], v[116:119]
	v_mfma_f32_16x16x32_bf16 v[112:115], v[156:159], v[194:197], v[112:115]
	v_mfma_f32_16x16x32_bf16 v[108:111], v[148:151], v[202:205], v[108:111]
	v_mfma_f32_16x16x32_bf16 v[104:107], v[156:159], v[202:205], v[104:107]
	v_mfma_f32_16x16x32_bf16 v[100:103], v[148:151], v[210:213], v[100:103]
	v_mfma_f32_16x16x32_bf16 v[96:99], v[156:159], v[210:213], v[96:99]
	v_mfma_f32_16x16x32_bf16 v[60:63], v[164:167], v[186:189], v[60:63]
	v_mfma_f32_16x16x32_bf16 v[56:59], v[178:181], v[186:189], v[56:59]
	v_mfma_f32_16x16x32_bf16 v[52:55], v[164:167], v[194:197], v[52:55]
	v_mfma_f32_16x16x32_bf16 v[48:51], v[178:181], v[194:197], v[48:51]
	v_mfma_f32_16x16x32_bf16 v[44:47], v[164:167], v[202:205], v[44:47]
	v_mfma_f32_16x16x32_bf16 v[40:43], v[178:181], v[202:205], v[40:43]
	v_mfma_f32_16x16x32_bf16 v[36:39], v[164:167], v[210:213], v[36:39]
	v_mfma_f32_16x16x32_bf16 v[32:35], v[178:181], v[210:213], v[32:35]
	s_setprio 0
	s_barrier
	s_add_i32 s14, s42, s27
	v_lshl_add_u64 v[214:215], s[18:19], 0, v[130:131]
	s_mov_b32 m0, s14
	ds_read_b128 v[182:185], v173 offset:16384
	ds_read_b128 v[186:189], v173 offset:17408
	ds_read_b128 v[190:193], v173 offset:18432
	ds_read_b128 v[194:197], v173 offset:19456
	ds_read_b128 v[198:201], v173 offset:20480
	ds_read_b128 v[202:205], v173 offset:21504
	ds_read_b128 v[206:209], v173 offset:22528
	ds_read_b128 v[210:213], v173 offset:23552
	global_load_lds_dwordx4 v[214:215], off
	s_add_i32 m0, s14, 0x2000
	s_add_u32 s14, s18, 0xb0000
	v_lshl_add_u64 v[216:217], s[18:19], 0, v[134:135]
	s_addc_u32 s15, s19, 0
	s_add_i32 s51, s43, s27
	global_load_lds_dwordx4 v[216:217], off
	v_lshl_add_u64 v[218:219], s[14:15], 0, v[130:131]
	s_mov_b32 m0, s51
	v_lshl_add_u64 v[220:221], s[20:21], 0, v[132:133]
	global_load_lds_dwordx4 v[218:219], off
	v_lshl_add_u64 v[218:219], s[14:15], 0, v[134:135]
	s_add_i32 m0, s51, 0x2000
	s_nop 0
	global_load_lds_dwordx4 v[218:219], off
	v_lshl_add_u64 v[218:219], s[20:21], 0, v[128:129]
	s_mov_b32 m0, s28
	s_nop 0
	global_load_lds_dwordx4 v[218:219], off
	s_mov_b32 m0, s29
	s_nop 0
	global_load_lds_dwordx4 v[220:221], off
	s_setprio 1
	s_waitcnt lgkmcnt(0)
	v_mfma_f32_16x16x32_bf16 v[92:95], v[144:147], v[182:185], v[92:95]
	s_waitcnt vmcnt(8)
	s_waitcnt lgkmcnt(0)
	s_barrier
	v_mfma_f32_16x16x32_bf16 v[88:91], v[152:155], v[182:185], v[88:91]
	v_mfma_f32_16x16x32_bf16 v[84:87], v[144:147], v[190:193], v[84:87]
	v_mfma_f32_16x16x32_bf16 v[80:83], v[152:155], v[190:193], v[80:83]
	v_mfma_f32_16x16x32_bf16 v[76:79], v[144:147], v[198:201], v[76:79]
	v_mfma_f32_16x16x32_bf16 v[72:75], v[152:155], v[198:201], v[72:75]
	v_mfma_f32_16x16x32_bf16 v[68:71], v[144:147], v[206:209], v[68:71]
	v_mfma_f32_16x16x32_bf16 v[64:67], v[152:155], v[206:209], v[64:67]
	v_mfma_f32_16x16x32_bf16 v[28:31], v[160:163], v[182:185], v[28:31]
	v_mfma_f32_16x16x32_bf16 v[24:27], v[174:177], v[182:185], v[24:27]
	v_mfma_f32_16x16x32_bf16 v[20:23], v[160:163], v[190:193], v[20:23]
	v_mfma_f32_16x16x32_bf16 v[16:19], v[174:177], v[190:193], v[16:19]
	v_mfma_f32_16x16x32_bf16 v[12:15], v[160:163], v[198:201], v[12:15]
	v_mfma_f32_16x16x32_bf16 v[8:11], v[174:177], v[198:201], v[8:11]
	v_mfma_f32_16x16x32_bf16 v[4:7], v[160:163], v[206:209], v[4:7]
	v_mfma_f32_16x16x32_bf16 v[0:3], v[174:177], v[206:209], v[0:3]
	v_mfma_f32_16x16x32_bf16 v[92:95], v[148:151], v[186:189], v[92:95]
	v_mfma_f32_16x16x32_bf16 v[88:91], v[156:159], v[186:189], v[88:91]
	v_mfma_f32_16x16x32_bf16 v[84:87], v[148:151], v[194:197], v[84:87]
	v_mfma_f32_16x16x32_bf16 v[80:83], v[156:159], v[194:197], v[80:83]
	v_mfma_f32_16x16x32_bf16 v[76:79], v[148:151], v[202:205], v[76:79]
	v_mfma_f32_16x16x32_bf16 v[72:75], v[156:159], v[202:205], v[72:75]
	v_mfma_f32_16x16x32_bf16 v[68:71], v[148:151], v[210:213], v[68:71]
	v_mfma_f32_16x16x32_bf16 v[64:67], v[156:159], v[210:213], v[64:67]
	v_mfma_f32_16x16x32_bf16 v[28:31], v[164:167], v[186:189], v[28:31]
	v_mfma_f32_16x16x32_bf16 v[24:27], v[178:181], v[186:189], v[24:27]
	v_mfma_f32_16x16x32_bf16 v[20:23], v[164:167], v[194:197], v[20:23]
	v_mfma_f32_16x16x32_bf16 v[16:19], v[178:181], v[194:197], v[16:19]
	v_mfma_f32_16x16x32_bf16 v[12:15], v[164:167], v[202:205], v[12:15]
	v_mfma_f32_16x16x32_bf16 v[8:11], v[178:181], v[202:205], v[8:11]
	v_mfma_f32_16x16x32_bf16 v[4:7], v[164:167], v[210:213], v[4:7]
	v_mfma_f32_16x16x32_bf16 v[0:3], v[178:181], v[210:213], v[0:3]
	s_setprio 0
	s_barrier
	s_add_i32 s51, 0, 0x18000
	s_add_i32 s52, 0, 0x1c000
	v_add_u32_e32 v156, s51, v170
	v_add_u32_e32 v178, s52, v170
	ds_read_b128 v[144:147], v156
	ds_read_b128 v[148:151], v156 offset:1024
	ds_read_b128 v[152:155], v156 offset:2048
	ds_read_b128 v[156:159], v156 offset:3072
	ds_read_b128 v[160:163], v178
	ds_read_b128 v[164:167], v178 offset:1024
	ds_read_b128 v[174:177], v178 offset:2048
	ds_read_b128 v[178:181], v178 offset:3072
	s_add_u32 s14, s20, 0xb0000
	s_addc_u32 s15, s21, 0
	s_mov_b32 m0, s30
	v_lshl_add_u64 v[222:223], s[14:15], 0, v[128:129]
	ds_read_b128 v[182:185], v173 offset:32768
	ds_read_b128 v[186:189], v173 offset:33792
	ds_read_b128 v[190:193], v173 offset:34816
	ds_read_b128 v[194:197], v173 offset:35840
	ds_read_b128 v[198:201], v173 offset:36864
	ds_read_b128 v[202:205], v173 offset:37888
	ds_read_b128 v[206:209], v173 offset:38912
	ds_read_b128 v[210:213], v173 offset:39936
	global_load_lds_dwordx4 v[222:223], off
	v_lshl_add_u64 v[222:223], s[14:15], 0, v[132:133]
	s_mov_b32 m0, s31
	s_nop 0
	global_load_lds_dwordx4 v[222:223], off
	s_setprio 1
	s_waitcnt lgkmcnt(0)
	v_mfma_f32_16x16x32_bf16 v[124:127], v[144:147], v[182:185], v[124:127]
	s_waitcnt vmcnt(8)
	s_waitcnt lgkmcnt(0)
	s_barrier
	v_mfma_f32_16x16x32_bf16 v[120:123], v[152:155], v[182:185], v[120:123]
	v_mfma_f32_16x16x32_bf16 v[116:119], v[144:147], v[190:193], v[116:119]
	v_mfma_f32_16x16x32_bf16 v[112:115], v[152:155], v[190:193], v[112:115]
	v_mfma_f32_16x16x32_bf16 v[108:111], v[144:147], v[198:201], v[108:111]
	v_mfma_f32_16x16x32_bf16 v[104:107], v[152:155], v[198:201], v[104:107]
	v_mfma_f32_16x16x32_bf16 v[100:103], v[144:147], v[206:209], v[100:103]
	v_mfma_f32_16x16x32_bf16 v[96:99], v[152:155], v[206:209], v[96:99]
	v_mfma_f32_16x16x32_bf16 v[60:63], v[160:163], v[182:185], v[60:63]
	v_mfma_f32_16x16x32_bf16 v[56:59], v[174:177], v[182:185], v[56:59]
	v_mfma_f32_16x16x32_bf16 v[52:55], v[160:163], v[190:193], v[52:55]
	v_mfma_f32_16x16x32_bf16 v[48:51], v[174:177], v[190:193], v[48:51]
	v_mfma_f32_16x16x32_bf16 v[44:47], v[160:163], v[198:201], v[44:47]
	v_mfma_f32_16x16x32_bf16 v[40:43], v[174:177], v[198:201], v[40:43]
	v_mfma_f32_16x16x32_bf16 v[36:39], v[160:163], v[206:209], v[36:39]
	v_mfma_f32_16x16x32_bf16 v[32:35], v[174:177], v[206:209], v[32:35]
	v_mfma_f32_16x16x32_bf16 v[124:127], v[148:151], v[186:189], v[124:127]
	v_mfma_f32_16x16x32_bf16 v[120:123], v[156:159], v[186:189], v[120:123]
	v_mfma_f32_16x16x32_bf16 v[116:119], v[148:151], v[194:197], v[116:119]
	v_mfma_f32_16x16x32_bf16 v[112:115], v[156:159], v[194:197], v[112:115]
	v_mfma_f32_16x16x32_bf16 v[108:111], v[148:151], v[202:205], v[108:111]
	v_mfma_f32_16x16x32_bf16 v[104:107], v[156:159], v[202:205], v[104:107]
	v_mfma_f32_16x16x32_bf16 v[100:103], v[148:151], v[210:213], v[100:103]
	v_mfma_f32_16x16x32_bf16 v[96:99], v[156:159], v[210:213], v[96:99]
	v_mfma_f32_16x16x32_bf16 v[60:63], v[164:167], v[186:189], v[60:63]
	v_mfma_f32_16x16x32_bf16 v[56:59], v[178:181], v[186:189], v[56:59]
	v_mfma_f32_16x16x32_bf16 v[52:55], v[164:167], v[194:197], v[52:55]
	v_mfma_f32_16x16x32_bf16 v[48:51], v[178:181], v[194:197], v[48:51]
	v_mfma_f32_16x16x32_bf16 v[44:47], v[164:167], v[202:205], v[44:47]
	v_mfma_f32_16x16x32_bf16 v[40:43], v[178:181], v[202:205], v[40:43]
	v_mfma_f32_16x16x32_bf16 v[36:39], v[164:167], v[210:213], v[36:39]
	v_mfma_f32_16x16x32_bf16 v[32:35], v[178:181], v[210:213], v[32:35]
	s_setprio 0
	s_barrier
	s_add_i32 s14, s51, s27
	v_lshl_add_u64 v[214:215], v[214:215], 0, s[8:9]
	s_mov_b32 m0, s14
	ds_read_b128 v[182:185], v173 offset:49152
	ds_read_b128 v[186:189], v173 offset:50176
	ds_read_b128 v[190:193], v173 offset:51200
	ds_read_b128 v[194:197], v173 offset:52224
	ds_read_b128 v[198:201], v173 offset:53248
	ds_read_b128 v[202:205], v173 offset:54272
	ds_read_b128 v[206:209], v173 offset:55296
	ds_read_b128 v[210:213], v173 offset:56320
	global_load_lds_dwordx4 v[214:215], off
	s_add_i32 m0, s14, 0x2000
	s_add_u32 s14, s18, 0xb0080
	v_lshl_add_u64 v[214:215], v[216:217], 0, s[8:9]
	s_addc_u32 s15, s19, 0
	s_add_i32 s18, s52, s27
	global_load_lds_dwordx4 v[214:215], off
	v_lshl_add_u64 v[214:215], s[14:15], 0, v[130:131]
	s_mov_b32 m0, s18
	s_nop 0
	global_load_lds_dwordx4 v[214:215], off
	v_lshl_add_u64 v[214:215], s[14:15], 0, v[134:135]
	s_add_i32 m0, s18, 0x2000
	s_nop 0
	global_load_lds_dwordx4 v[214:215], off
	v_lshl_add_u64 v[214:215], v[218:219], 0, s[8:9]
	s_mov_b32 m0, s39
	s_nop 0
	global_load_lds_dwordx4 v[214:215], off
	v_lshl_add_u64 v[214:215], v[220:221], 0, s[8:9]
	s_mov_b32 m0, s40
	s_nop 0
	global_load_lds_dwordx4 v[214:215], off
	s_setprio 1
	s_waitcnt lgkmcnt(0)
	v_mfma_f32_16x16x32_bf16 v[92:95], v[144:147], v[182:185], v[92:95]
	s_waitcnt vmcnt(8)
	s_waitcnt lgkmcnt(0)
	s_barrier
	v_mfma_f32_16x16x32_bf16 v[88:91], v[152:155], v[182:185], v[88:91]
	v_mfma_f32_16x16x32_bf16 v[84:87], v[144:147], v[190:193], v[84:87]
	v_mfma_f32_16x16x32_bf16 v[80:83], v[152:155], v[190:193], v[80:83]
	v_mfma_f32_16x16x32_bf16 v[76:79], v[144:147], v[198:201], v[76:79]
	v_mfma_f32_16x16x32_bf16 v[72:75], v[152:155], v[198:201], v[72:75]
	v_mfma_f32_16x16x32_bf16 v[68:71], v[144:147], v[206:209], v[68:71]
	v_mfma_f32_16x16x32_bf16 v[64:67], v[152:155], v[206:209], v[64:67]
	v_mfma_f32_16x16x32_bf16 v[28:31], v[160:163], v[182:185], v[28:31]
	v_mfma_f32_16x16x32_bf16 v[24:27], v[174:177], v[182:185], v[24:27]
	v_mfma_f32_16x16x32_bf16 v[20:23], v[160:163], v[190:193], v[20:23]
	v_mfma_f32_16x16x32_bf16 v[16:19], v[174:177], v[190:193], v[16:19]
	v_mfma_f32_16x16x32_bf16 v[12:15], v[160:163], v[198:201], v[12:15]
	v_mfma_f32_16x16x32_bf16 v[8:11], v[174:177], v[198:201], v[8:11]
	v_mfma_f32_16x16x32_bf16 v[4:7], v[160:163], v[206:209], v[4:7]
	v_mfma_f32_16x16x32_bf16 v[0:3], v[174:177], v[206:209], v[0:3]
	v_mfma_f32_16x16x32_bf16 v[92:95], v[148:151], v[186:189], v[92:95]
	v_mfma_f32_16x16x32_bf16 v[88:91], v[156:159], v[186:189], v[88:91]
	v_mfma_f32_16x16x32_bf16 v[84:87], v[148:151], v[194:197], v[84:87]
	v_mfma_f32_16x16x32_bf16 v[80:83], v[156:159], v[194:197], v[80:83]
	v_mfma_f32_16x16x32_bf16 v[76:79], v[148:151], v[202:205], v[76:79]
	v_mfma_f32_16x16x32_bf16 v[72:75], v[156:159], v[202:205], v[72:75]
	v_mfma_f32_16x16x32_bf16 v[68:71], v[148:151], v[210:213], v[68:71]
	v_mfma_f32_16x16x32_bf16 v[64:67], v[156:159], v[210:213], v[64:67]
	v_mfma_f32_16x16x32_bf16 v[28:31], v[164:167], v[186:189], v[28:31]
	v_mfma_f32_16x16x32_bf16 v[24:27], v[178:181], v[186:189], v[24:27]
	v_mfma_f32_16x16x32_bf16 v[20:23], v[164:167], v[194:197], v[20:23]
	v_mfma_f32_16x16x32_bf16 v[16:19], v[178:181], v[194:197], v[16:19]
	v_mfma_f32_16x16x32_bf16 v[12:15], v[164:167], v[202:205], v[12:15]
	v_mfma_f32_16x16x32_bf16 v[8:11], v[178:181], v[202:205], v[8:11]
	v_mfma_f32_16x16x32_bf16 v[4:7], v[164:167], v[210:213], v[4:7]
	v_mfma_f32_16x16x32_bf16 v[0:3], v[178:181], v[210:213], v[0:3]
	s_setprio 0
	s_add_i32 s50, s50, 2
	s_add_u32 s48, s48, 0x100
	s_addc_u32 s49, s49, 0
	s_cmp_gt_u32 s50, 41
	s_mov_b64 s[14:15], s[16:17]
	s_barrier
	s_cbranch_scc0 .LBB0_1002
	s_and_b64 vcc, exec, s[10:11]
	s_cbranch_vccz .LBB0_1005
	s_barrier
